# stack + up-phase epilogue-1 gate loads software-pipelined
# speedup vs baseline: 1.0249x; 1.0067x over previous
; DI void gemm8_accum(f32x4 (&acc)[8][4], const bf16_t* a, size_t lda, const bf16_t* b, size_t ldb, int nkb, bf16_t* L,
;                     const bool pre, const bf16_t* an, size_t ldan, const bf16_t* bn, size_t ldbn) {
;     ...
;   __syncthreads();
;   g8_store1(L + 32768, ra, lrow, lch);
;   g8_load1(ra, an, ldan, 0, lrow, lch);
;   __builtin_amdgcn_sched_barrier(0);
;   g8_compute<0, 1>(acc, L, wm, wn, lane);
;   __builtin_amdgcn_sched_barrier(0);
;   g8_store1(L + 32768 + 16384, rb, lrow, lch);
;   g8_load1(rb, bn, ldbn, 0, lrow, lch);
;   __builtin_amdgcn_sched_barrier(0);
;   g8_compute<1, 2>(acc, L, wm, wn, lane);
;   __syncthreads();
;   g8_store1(L, ra, lrow, lch);
;   __builtin_amdgcn_sched_barrier(0);
;   g8_compute<0, 1>(acc, L + 32768, wm, wn, lane);
;   __builtin_amdgcn_sched_barrier(0);
;   g8_store1(L + 16384, rb, lrow, lch);
;   __builtin_amdgcn_sched_barrier(0);
;   g8_compute<1, 2>(acc, L + 32768, wm, wn, lane);
.Lstg_778_c:
	s_mul_i32 s0, s13, 0x2a30
	s_movk_i32 s25, 0x1518
	s_add_u32 s2, s16, s0
	v_mad_u64_u32 v[180:181], s[0:1], v190, s25, v[170:171]
	s_addc_u32 s3, s17, 0
	v_mov_b32_e32 v181, v1
	v_lshl_add_u64 v[172:173], v[180:181], 1, s[2:3]
	v_add_u32_e32 v174, 0x54600, v180
	v_mov_b32_e32 v175, v1
	v_add_u32_e32 v182, 0xa8c00, v180
	v_mov_b32_e32 v183, v1
	v_add_u32_e32 v180, 0xfd200, v180
	v_lshl_add_u64 v[176:177], v[174:175], 1, s[2:3]
	v_lshl_add_u64 v[182:183], v[182:183], 1, s[2:3]
	v_lshl_add_u64 v[184:185], v[180:181], 1, s[2:3]
	s_barrier
	global_load_dwordx4 v[172:175], v[172:173], off offset:2608
	s_nop 0
	global_load_dwordx4 v[176:179], v[176:177], off offset:2608
	s_nop 0
	global_load_dwordx4 v[180:183], v[182:183], off offset:2608
	s_nop 0
	global_load_dwordx4 v[184:187], v[184:185], off offset:2608
	s_mul_i32 s0, s7, 0x2a3000
	s_lshl_b32 s1, s6, 1
	v_readlane_b32 s6, v252, 1
	v_readlane_b32 s7, v252, 2
	s_add_u32 s6, s6, s1
	s_addc_u32 s7, s7, 0
	s_add_i32 s20, 0, 0x10000
	v_add3_u32 v170, s20, v165, v167
	s_waitcnt vmcnt(11)
	ds_write_b128 v170, v[22:25]
	s_waitcnt vmcnt(9)
	ds_write_b128 v170, v[18:21] offset:8192
	ds_write_b128 v170, v[26:29] offset:16384
	s_waitcnt vmcnt(8)
	ds_write_b128 v170, v[30:33] offset:24576
	v_lshlrev_b32_e32 v170, 1, v169
	v_add_u32_e32 v169, 0, v170
	v_add_u32_e32 v194, v169, v188
	ds_read_b128 v[18:21], v194
	ds_read_b128 v[22:25], v194 offset:2048
	ds_read_b128 v[26:29], v194 offset:4096
	ds_read_b128 v[30:33], v194 offset:6144
	ds_read_b128 v[190:193], v194 offset:8192
	ds_read_b128 v[198:201], v194 offset:10240
	ds_read_b128 v[206:209], v194 offset:12288
	ds_read_b128 v[210:213], v194 offset:14336
	v_add_u32_e32 v169, v169, v171
	ds_read_b128 v[214:217], v169 offset:32768
	ds_read_b128 v[218:221], v169 offset:34816
	ds_read_b128 v[222:225], v169 offset:36864
	ds_read_b128 v[226:229], v169 offset:38912
	s_setprio 1
	s_waitcnt lgkmcnt(3)
	v_mfma_f32_16x16x32_bf16 v[158:161], v[214:217], v[18:21], v[158:161]
	s_waitcnt lgkmcnt(2)
	v_mfma_f32_16x16x32_bf16 v[154:157], v[218:221], v[18:21], v[154:157]
	s_waitcnt lgkmcnt(1)
	v_mfma_f32_16x16x32_bf16 v[150:153], v[222:225], v[18:21], v[150:153]
	s_waitcnt lgkmcnt(0)
	v_mfma_f32_16x16x32_bf16 v[18:21], v[226:229], v[18:21], v[146:149]
	v_mfma_f32_16x16x32_bf16 v[142:145], v[214:217], v[22:25], v[142:145]
	v_mfma_f32_16x16x32_bf16 v[138:141], v[218:221], v[22:25], v[138:141]
	v_mfma_f32_16x16x32_bf16 v[134:137], v[222:225], v[22:25], v[134:137]
	v_mfma_f32_16x16x32_bf16 v[22:25], v[226:229], v[22:25], v[130:133]
	v_mfma_f32_16x16x32_bf16 v[126:129], v[214:217], v[26:29], v[126:129]
	v_mfma_f32_16x16x32_bf16 v[122:125], v[218:221], v[26:29], v[122:125]
	v_mfma_f32_16x16x32_bf16 v[118:121], v[222:225], v[26:29], v[118:121]
	v_mfma_f32_16x16x32_bf16 v[26:29], v[226:229], v[26:29], v[114:117]
	v_mfma_f32_16x16x32_bf16 v[110:113], v[214:217], v[30:33], v[110:113]
	v_mfma_f32_16x16x32_bf16 v[106:109], v[218:221], v[30:33], v[106:109]
	v_mfma_f32_16x16x32_bf16 v[102:105], v[222:225], v[30:33], v[102:105]
	v_mfma_f32_16x16x32_bf16 v[30:33], v[226:229], v[30:33], v[98:101]
	v_mfma_f32_16x16x32_bf16 v[94:97], v[214:217], v[190:193], v[94:97]
	v_mfma_f32_16x16x32_bf16 v[90:93], v[218:221], v[190:193], v[90:93]
	v_mfma_f32_16x16x32_bf16 v[86:89], v[222:225], v[190:193], v[86:89]
	v_mfma_f32_16x16x32_bf16 v[82:85], v[226:229], v[190:193], v[82:85]
	v_mfma_f32_16x16x32_bf16 v[78:81], v[214:217], v[198:201], v[78:81]
	v_mfma_f32_16x16x32_bf16 v[74:77], v[218:221], v[198:201], v[74:77]
	v_mfma_f32_16x16x32_bf16 v[70:73], v[222:225], v[198:201], v[70:73]
	v_mfma_f32_16x16x32_bf16 v[66:69], v[226:229], v[198:201], v[66:69]
	v_mfma_f32_16x16x32_bf16 v[62:65], v[214:217], v[206:209], v[62:65]
	v_mfma_f32_16x16x32_bf16 v[58:61], v[218:221], v[206:209], v[58:61]
	v_mfma_f32_16x16x32_bf16 v[54:57], v[222:225], v[206:209], v[54:57]
	v_mfma_f32_16x16x32_bf16 v[50:53], v[226:229], v[206:209], v[50:53]
	v_mfma_f32_16x16x32_bf16 v[46:49], v[214:217], v[210:213], v[46:49]
	v_mfma_f32_16x16x32_bf16 v[42:45], v[218:221], v[210:213], v[42:45]
	v_mfma_f32_16x16x32_bf16 v[38:41], v[222:225], v[210:213], v[38:41]
	v_mfma_f32_16x16x32_bf16 v[34:37], v[226:229], v[210:213], v[34:37]
	s_setprio 0
	v_readlane_b32 s1, v254, 36
	v_mov_b32_e32 v169, v1
	s_nop 0
	v_add3_u32 v98, s1, v165, v167
	v_mov_b32_e32 v167, v1
	v_mov_b32_e32 v165, v1
	s_waitcnt vmcnt(7)
	ds_write_b128 v98, v[14:17]
	s_waitcnt vmcnt(6)
	ds_write_b128 v98, v[2:5] offset:8192
	s_waitcnt vmcnt(5)
	ds_write_b128 v98, v[6:9] offset:16384
	s_waitcnt vmcnt(4)
	ds_write_b128 v98, v[10:13] offset:24576
	v_lshl_add_u64 v[2:3], v[0:1], 1, s[6:7]
	v_lshl_add_u64 v[6:7], v[168:169], 1, s[6:7]
	v_lshl_add_u64 v[10:11], v[166:167], 1, s[6:7]
	v_lshl_add_u64 v[14:15], v[164:165], 1, s[6:7]
	global_load_dwordx4 v[2:5], v[2:3], off
	s_nop 0
	global_load_dwordx4 v[6:9], v[6:7], off
	s_nop 0
	global_load_dwordx4 v[10:13], v[10:11], off
	s_nop 0
	global_load_dwordx4 v[14:17], v[14:15], off
	v_lshlrev_b32_e32 v0, 1, v189
	v_add_u32_e32 v168, 0, v0
	v_add_u32_e32 v169, v168, v188
	ds_read_b128 v[98:101], v169
	ds_read_b128 v[114:117], v169 offset:2048
	ds_read_b128 v[130:133], v169 offset:4096
	ds_read_b128 v[146:149], v169 offset:6144
	ds_read_b128 v[164:167], v169 offset:8192
	ds_read_b128 v[190:193], v169 offset:10240
	ds_read_b128 v[198:201], v169 offset:12288
	ds_read_b128 v[206:209], v169 offset:14336
	v_add_u32_e32 v168, v168, v171
	ds_read_b128 v[210:213], v168 offset:32768
	ds_read_b128 v[214:217], v168 offset:34816
	ds_read_b128 v[218:221], v168 offset:36864
	ds_read_b128 v[222:225], v168 offset:38912
	s_setprio 1
	s_waitcnt lgkmcnt(3)
; DI void gemm8_accum(f32x4 (&acc)[8][4], const bf16_t* a, size_t lda, const bf16_t* b, size_t ldb, int nkb, bf16_t* L,
;                     const bool pre, const bf16_t* an, size_t ldan, const bf16_t* bn, size_t ldbn) {
;     ...
;   __syncthreads();
;   g8_store1(L + 32768, ra, lrow, lch);
;   g8_load1(ra, an, ldan, 0, lrow, lch);
;   __builtin_amdgcn_sched_barrier(0);
;   g8_compute<0, 1>(acc, L, wm, wn, lane);
;   __builtin_amdgcn_sched_barrier(0);
;   g8_store1(L + 32768 + 16384, rb, lrow, lch);
;   g8_load1(rb, bn, ldbn, 0, lrow, lch);
;   __builtin_amdgcn_sched_barrier(0);
;   g8_compute<1, 2>(acc, L, wm, wn, lane);
;   __syncthreads();
;   g8_store1(L, ra, lrow, lch);
;   __builtin_amdgcn_sched_barrier(0);
;   g8_compute<0, 1>(acc, L + 32768, wm, wn, lane);
;   __builtin_amdgcn_sched_barrier(0);
;   g8_store1(L + 16384, rb, lrow, lch);
;   __builtin_amdgcn_sched_barrier(0);
;   g8_compute<1, 2>(acc, L + 32768, wm, wn, lane);
	v_mfma_f32_16x16x32_bf16 v[158:161], v[210:213], v[98:101], v[158:161]
	s_waitcnt lgkmcnt(2)
	v_mfma_f32_16x16x32_bf16 v[154:157], v[214:217], v[98:101], v[154:157]
	s_waitcnt lgkmcnt(1)
	v_mfma_f32_16x16x32_bf16 v[150:153], v[218:221], v[98:101], v[150:153]
	s_waitcnt lgkmcnt(0)
	v_mfma_f32_16x16x32_bf16 v[18:21], v[222:225], v[98:101], v[18:21]
	v_mfma_f32_16x16x32_bf16 v[98:101], v[210:213], v[114:117], v[142:145]
	v_mfma_f32_16x16x32_bf16 v[138:141], v[214:217], v[114:117], v[138:141]
	v_mfma_f32_16x16x32_bf16 v[134:137], v[218:221], v[114:117], v[134:137]
	v_mfma_f32_16x16x32_bf16 v[22:25], v[222:225], v[114:117], v[22:25]
	v_mfma_f32_16x16x32_bf16 v[114:117], v[210:213], v[130:133], v[126:129]
	v_mfma_f32_16x16x32_bf16 v[122:125], v[214:217], v[130:133], v[122:125]
	v_mfma_f32_16x16x32_bf16 v[118:121], v[218:221], v[130:133], v[118:121]
	v_mfma_f32_16x16x32_bf16 v[26:29], v[222:225], v[130:133], v[26:29]
	v_mfma_f32_16x16x32_bf16 v[110:113], v[210:213], v[146:149], v[110:113]
	v_mfma_f32_16x16x32_bf16 v[106:109], v[214:217], v[146:149], v[106:109]
	v_mfma_f32_16x16x32_bf16 v[102:105], v[218:221], v[146:149], v[102:105]
	v_mfma_f32_16x16x32_bf16 v[30:33], v[222:225], v[146:149], v[30:33]
	v_mfma_f32_16x16x32_bf16 v[94:97], v[210:213], v[164:167], v[94:97]
	v_mfma_f32_16x16x32_bf16 v[90:93], v[214:217], v[164:167], v[90:93]
	v_mfma_f32_16x16x32_bf16 v[86:89], v[218:221], v[164:167], v[86:89]
	v_mfma_f32_16x16x32_bf16 v[82:85], v[222:225], v[164:167], v[82:85]
	v_mfma_f32_16x16x32_bf16 v[78:81], v[210:213], v[190:193], v[78:81]
	v_mfma_f32_16x16x32_bf16 v[74:77], v[214:217], v[190:193], v[74:77]
	v_mfma_f32_16x16x32_bf16 v[70:73], v[218:221], v[190:193], v[70:73]
	v_mfma_f32_16x16x32_bf16 v[66:69], v[222:225], v[190:193], v[66:69]
	v_mfma_f32_16x16x32_bf16 v[62:65], v[210:213], v[198:201], v[62:65]
	v_mfma_f32_16x16x32_bf16 v[58:61], v[214:217], v[198:201], v[58:61]
	v_mfma_f32_16x16x32_bf16 v[54:57], v[218:221], v[198:201], v[54:57]
	v_mfma_f32_16x16x32_bf16 v[50:53], v[222:225], v[198:201], v[50:53]
	v_mfma_f32_16x16x32_bf16 v[46:49], v[210:213], v[206:209], v[46:49]
	v_mfma_f32_16x16x32_bf16 v[42:45], v[214:217], v[206:209], v[42:45]
	v_mfma_f32_16x16x32_bf16 v[38:41], v[218:221], v[206:209], v[38:41]
	v_mfma_f32_16x16x32_bf16 v[34:37], v[222:225], v[206:209], v[34:37]
	s_setprio 0
	s_barrier
	s_waitcnt vmcnt(7)
	ds_write_b128 v163, v[172:175]
	s_waitcnt vmcnt(6)
	ds_write_b128 v163, v[176:179] offset:8192
	s_waitcnt vmcnt(5)
	ds_write_b128 v163, v[180:183] offset:16384
	s_waitcnt vmcnt(4)
	ds_write_b128 v163, v[184:187] offset:24576
	v_add3_u32 v168, s20, v170, v188
	ds_read_b128 v[126:129], v168
	ds_read_b128 v[130:133], v168 offset:2048
	ds_read_b128 v[142:145], v168 offset:4096
	ds_read_b128 v[146:149], v168 offset:6144
	ds_read_b128 v[164:167], v168 offset:8192
	ds_read_b128 v[172:175], v168 offset:10240
	ds_read_b128 v[176:179], v168 offset:12288
	ds_read_b128 v[180:183], v168 offset:14336
	v_add3_u32 v168, s1, v170, v171
	ds_read_b128 v[184:187], v168
	ds_read_b128 v[190:193], v168 offset:2048
	ds_read_b128 v[198:201], v168 offset:4096
	ds_read_b128 v[206:209], v168 offset:6144
	s_setprio 1
	s_waitcnt lgkmcnt(3)
	v_mfma_f32_16x16x32_bf16 v[158:161], v[184:187], v[126:129], v[158:161]
	s_waitcnt lgkmcnt(2)
	v_mfma_f32_16x16x32_bf16 v[154:157], v[190:193], v[126:129], v[154:157]
	s_waitcnt lgkmcnt(1)
	v_mfma_f32_16x16x32_bf16 v[150:153], v[198:201], v[126:129], v[150:153]
	s_waitcnt lgkmcnt(0)
	v_mfma_f32_16x16x32_bf16 v[18:21], v[206:209], v[126:129], v[18:21]
	v_mfma_f32_16x16x32_bf16 v[98:101], v[184:187], v[130:133], v[98:101]
	v_mfma_f32_16x16x32_bf16 v[126:129], v[190:193], v[130:133], v[138:141]
	v_mfma_f32_16x16x32_bf16 v[134:137], v[198:201], v[130:133], v[134:137]
	v_mfma_f32_16x16x32_bf16 v[130:133], v[206:209], v[130:133], v[22:25]
	v_mfma_f32_16x16x32_bf16 v[114:117], v[184:187], v[142:145], v[114:117]
	v_mfma_f32_16x16x32_bf16 v[122:125], v[190:193], v[142:145], v[122:125]
	v_mfma_f32_16x16x32_bf16 v[118:121], v[198:201], v[142:145], v[118:121]
	v_mfma_f32_16x16x32_bf16 v[26:29], v[206:209], v[142:145], v[26:29]
	v_mfma_f32_16x16x32_bf16 v[110:113], v[184:187], v[146:149], v[110:113]
	v_mfma_f32_16x16x32_bf16 v[106:109], v[190:193], v[146:149], v[106:109]
	v_mfma_f32_16x16x32_bf16 v[102:105], v[198:201], v[146:149], v[102:105]
	v_mfma_f32_16x16x32_bf16 v[138:141], v[206:209], v[146:149], v[30:33]
	v_mfma_f32_16x16x32_bf16 v[142:145], v[184:187], v[164:167], v[94:97]
	v_mfma_f32_16x16x32_bf16 v[90:93], v[190:193], v[164:167], v[90:93]
	v_mfma_f32_16x16x32_bf16 v[146:149], v[198:201], v[164:167], v[86:89]
	v_mfma_f32_16x16x32_bf16 v[82:85], v[206:209], v[164:167], v[82:85]
	v_mfma_f32_16x16x32_bf16 v[164:167], v[184:187], v[172:175], v[78:81]
	v_mfma_f32_16x16x32_bf16 v[74:77], v[190:193], v[172:175], v[74:77]
	v_mfma_f32_16x16x32_bf16 v[210:213], v[198:201], v[172:175], v[70:73]
	v_mfma_f32_16x16x32_bf16 v[66:69], v[206:209], v[172:175], v[66:69]
	v_mfma_f32_16x16x32_bf16 v[172:175], v[184:187], v[176:179], v[62:65]
	v_mfma_f32_16x16x32_bf16 v[58:61], v[190:193], v[176:179], v[58:61]
	v_mfma_f32_16x16x32_bf16 v[214:217], v[198:201], v[176:179], v[54:57]
	v_mfma_f32_16x16x32_bf16 v[50:53], v[206:209], v[176:179], v[50:53]
	v_mfma_f32_16x16x32_bf16 v[176:179], v[184:187], v[180:183], v[46:49]
	v_mfma_f32_16x16x32_bf16 v[184:187], v[190:193], v[180:183], v[42:45]
	v_mfma_f32_16x16x32_bf16 v[190:193], v[198:201], v[180:183], v[38:41]
	v_mfma_f32_16x16x32_bf16 v[180:183], v[206:209], v[180:183], v[34:37]
	s_setprio 0
	s_waitcnt vmcnt(3)
	ds_write_b128 v163, v[2:5] offset:32768
	s_waitcnt vmcnt(2)
; DI float bflo(unsigned u) { return __uint_as_float(u << 16); }
; DI float bfhi(unsigned u) { return __uint_as_float(u & 0xffff0000u); }
; DI float sigmoidf(float x) { return __builtin_amdgcn_rcpf(1.f + __expf(-x)); }
; DI float inv_sigmoidf(float x) { return 1.f + __expf(-x); }
; DI void gemm8_accum(f32x4 (&acc)[8][4], const bf16_t* a, size_t lda, const bf16_t* b, size_t ldb, int nkb, bf16_t* L,
;                     const bool pre, const bf16_t* an, size_t ldan, const bf16_t* bn, size_t ldbn) {
;     ...
;   g8_compute<1, 2>(acc, L, wm, wn, lane);
;   __syncthreads();
;   g8_store1(L, ra, lrow, lch);
;   __builtin_amdgcn_sched_barrier(0);
;   g8_compute<0, 1>(acc, L + 32768, wm, wn, lane);
;   __builtin_amdgcn_sched_barrier(0);
;   g8_store1(L + 16384, rb, lrow, lch);
;   __builtin_amdgcn_sched_barrier(0);
;   g8_compute<1, 2>(acc, L + 32768, wm, wn, lane);
; __global__ void __launch_bounds__(512, 2) mega(Params p) {
;     ...
;       gemm8_epi(acc8, m0, n0, [&](int m, int n, f32x4& a) {
;         uint2 ua = *(const uint2*)(z + (size_t)m * ZS + C_MA + n);
;         uint2 ub = *(const uint2*)(z + (size_t)m * ZS + C_MB + n);
;         a[0] *= sigmoidf(bflo(ua.x)) * inv_sigmoidf(bflo(ub.x));
;         a[1] *= sigmoidf(bfhi(ua.x)) * inv_sigmoidf(bfhi(ub.x));
;         a[2] *= sigmoidf(bflo(ua.y)) * inv_sigmoidf(bflo(ub.y));
;         a[3] *= sigmoidf(bfhi(ua.y)) * inv_sigmoidf(bfhi(ub.y));
	ds_write_b128 v163, v[6:9] offset:40960
	s_waitcnt vmcnt(1)
	ds_write_b128 v163, v[10:13] offset:49152
	s_waitcnt vmcnt(0)
	ds_write_b128 v163, v[14:17] offset:57344
	v_add3_u32 v6, s20, v0, v188
	ds_read_b128 v[2:5], v6
	ds_read_b128 v[34:37], v6 offset:2048
	ds_read_b128 v[42:45], v6 offset:4096
	ds_read_b128 v[198:201], v6 offset:6144
	ds_read_b128 v[206:209], v6 offset:8192
	ds_read_b128 v[218:221], v6 offset:10240
	ds_read_b128 v[222:225], v6 offset:12288
	ds_read_b128 v[226:229], v6 offset:14336
	v_add3_u32 v0, s1, v0, v171
	ds_read_b128 v[168:171], v0
	ds_read_b128 v[230:233], v0 offset:2048
	ds_read_b128 v[234:237], v0 offset:4096
	ds_read_b128 v[238:241], v0 offset:6144
	s_setprio 1
	s_waitcnt lgkmcnt(3)
	v_mfma_f32_16x16x32_bf16 v[158:161], v[168:171], v[2:5], v[158:161]
	s_waitcnt lgkmcnt(2)
	v_mfma_f32_16x16x32_bf16 v[6:9], v[230:233], v[2:5], v[154:157]
	s_waitcnt lgkmcnt(1)
	v_mfma_f32_16x16x32_bf16 v[10:13], v[234:237], v[2:5], v[150:153]
	s_waitcnt lgkmcnt(0)
	v_mfma_f32_16x16x32_bf16 v[14:17], v[238:241], v[2:5], v[18:21]
	v_mfma_f32_16x16x32_bf16 v[22:25], v[168:171], v[34:37], v[98:101]
	v_mfma_f32_16x16x32_bf16 v[30:33], v[230:233], v[34:37], v[126:129]
	v_mfma_f32_16x16x32_bf16 v[38:41], v[234:237], v[34:37], v[134:137]
	v_mfma_f32_16x16x32_bf16 v[46:49], v[238:241], v[34:37], v[130:133]
	v_mfma_f32_16x16x32_bf16 v[54:57], v[168:171], v[42:45], v[114:117]
	v_mfma_f32_16x16x32_bf16 v[62:65], v[230:233], v[42:45], v[122:125]
	v_mfma_f32_16x16x32_bf16 v[70:73], v[234:237], v[42:45], v[118:121]
	v_mfma_f32_16x16x32_bf16 v[78:81], v[238:241], v[42:45], v[26:29]
	v_mfma_f32_16x16x32_bf16 v[86:89], v[168:171], v[198:201], v[110:113]
	v_mfma_f32_16x16x32_bf16 v[94:97], v[230:233], v[198:201], v[106:109]
	v_mfma_f32_16x16x32_bf16 v[102:105], v[234:237], v[198:201], v[102:105]
	v_mfma_f32_16x16x32_bf16 v[110:113], v[238:241], v[198:201], v[138:141]
	v_mfma_f32_16x16x32_bf16 v[118:121], v[168:171], v[206:209], v[142:145]
	v_mfma_f32_16x16x32_bf16 v[126:129], v[230:233], v[206:209], v[90:93]
	v_mfma_f32_16x16x32_bf16 v[122:125], v[234:237], v[206:209], v[146:149]
	v_mfma_f32_16x16x32_bf16 v[114:117], v[238:241], v[206:209], v[82:85]
	v_mfma_f32_16x16x32_bf16 v[106:109], v[168:171], v[218:221], v[164:167]
	v_mfma_f32_16x16x32_bf16 v[98:101], v[230:233], v[218:221], v[74:77]
	v_mfma_f32_16x16x32_bf16 v[90:93], v[234:237], v[218:221], v[210:213]
	v_mfma_f32_16x16x32_bf16 v[82:85], v[238:241], v[218:221], v[66:69]
	v_mfma_f32_16x16x32_bf16 v[74:77], v[168:171], v[222:225], v[172:175]
	v_mfma_f32_16x16x32_bf16 v[66:69], v[230:233], v[222:225], v[58:61]
	v_mfma_f32_16x16x32_bf16 v[58:61], v[234:237], v[222:225], v[214:217]
	v_mfma_f32_16x16x32_bf16 v[50:53], v[238:241], v[222:225], v[50:53]
	v_mfma_f32_16x16x32_bf16 v[42:45], v[168:171], v[226:229], v[176:179]
	v_mfma_f32_16x16x32_bf16 v[34:37], v[230:233], v[226:229], v[184:187]
	v_mfma_f32_16x16x32_bf16 v[26:29], v[234:237], v[226:229], v[190:193]
	v_mfma_f32_16x16x32_bf16 v[18:21], v[238:241], v[226:229], v[180:183]
	s_setprio 0
	v_mov_b32_e32 v0, v196
	s_barrier
	v_mov_b64_e32 v[136:137], s[16:17]
	v_ashrrev_i32_e32 v3, 1, v0
	v_and_b32_e32 v2, 0xc0, v0
	v_and_b32_e32 v3, 0xffffff80, v3
	v_and_or_b32 v4, v0, 15, s13
	v_lshrrev_b32_e32 v0, 2, v0
	v_add_u32_e32 v142, v4, v3
	v_and_b32_e32 v0, 12, v0
	v_or3_b32 v0, v2, v0, s12
	v_mad_i64_i32 v[2:3], s[26:27], v142, s35, v[136:137]
	s_mov_b64 s[30:31], 0x1a30
	s_mov_b64 s[42:43], 0x2230
	v_lshl_add_u64 v[138:139], v[2:3], 0, s[30:31]
	v_lshlrev_b32_e32 v0, 1, v0
	v_lshl_add_u64 v[140:141], v[2:3], 0, s[42:43]
	v_lshl_add_u64 v[4:5], v[138:139], 0, v[0:1]
	v_lshl_add_u64 v[2:3], v[140:141], 0, v[0:1]
	s_mov_b32 s88, 0x2a300
	s_mov_b32 s89, 0
	v_mov_b64_e32 v[246:247], v[4:5]
	global_load_dwordx2 v[198:199], v[246:247], off
	global_load_dwordx2 v[200:201], v[246:247], off offset:2048
	global_load_dwordx2 v[202:203], v[246:247], off offset:32
	global_load_dwordx2 v[204:205], v[246:247], off offset:2080
	global_load_dwordx2 v[206:207], v[246:247], off offset:64
	global_load_dwordx2 v[208:209], v[246:247], off offset:2112
	global_load_dwordx2 v[210:211], v[246:247], off offset:96
	global_load_dwordx2 v[212:213], v[246:247], off offset:2144
	v_lshl_add_u64 v[246:247], v[246:247], 0, s[88:89]
	global_load_dwordx2 v[214:215], v[246:247], off
	global_load_dwordx2 v[216:217], v[246:247], off offset:2048
	global_load_dwordx2 v[218:219], v[246:247], off offset:32
	global_load_dwordx2 v[220:221], v[246:247], off offset:2080
	global_load_dwordx2 v[222:223], v[246:247], off offset:64
	global_load_dwordx2 v[224:225], v[246:247], off offset:2112
	global_load_dwordx2 v[226:227], v[246:247], off offset:96
	global_load_dwordx2 v[228:229], v[246:247], off offset:2144
	v_lshl_add_u64 v[246:247], v[246:247], 0, s[88:89]
	global_load_dwordx2 v[230:231], v[246:247], off
	global_load_dwordx2 v[232:233], v[246:247], off offset:2048
	global_load_dwordx2 v[234:235], v[246:247], off offset:32
	global_load_dwordx2 v[236:237], v[246:247], off offset:2080
	global_load_dwordx2 v[238:239], v[246:247], off offset:64
	global_load_dwordx2 v[240:241], v[246:247], off offset:2112
	global_load_dwordx2 v[242:243], v[246:247], off offset:96
	global_load_dwordx2 v[244:245], v[246:247], off offset:2144
	s_waitcnt vmcnt(23)
	v_mov_b64_e32 v[4:5], v[198:199]
	v_lshl_add_u64 v[246:247], v[246:247], 0, s[88:89]
	global_load_dwordx2 v[198:199], v[246:247], off
	v_or_b32_e32 v134, 32, v0
	s_waitcnt vmcnt(23)
; DI float bflo(unsigned u) { return __uint_as_float(u << 16); }
; DI float bfhi(unsigned u) { return __uint_as_float(u & 0xffff0000u); }
; DI float sigmoidf(float x) { return __builtin_amdgcn_rcpf(1.f + __expf(-x)); }
; DI float inv_sigmoidf(float x) { return 1.f + __expf(-x); }
; __global__ void __launch_bounds__(512, 2) mega(Params p) {
;     ...
;       gemm8_epi(acc8, m0, n0, [&](int m, int n, f32x4& a) {
;         uint2 ua = *(const uint2*)(z + (size_t)m * ZS + C_MA + n);
;         uint2 ub = *(const uint2*)(z + (size_t)m * ZS + C_MB + n);
;         a[0] *= sigmoidf(bflo(ua.x)) * inv_sigmoidf(bflo(ub.x));
;         a[1] *= sigmoidf(bfhi(ua.x)) * inv_sigmoidf(bfhi(ub.x));
;         a[2] *= sigmoidf(bflo(ua.y)) * inv_sigmoidf(bflo(ub.y));
;         a[3] *= sigmoidf(bfhi(ua.y)) * inv_sigmoidf(bfhi(ub.y));
;       });
	v_mov_b64_e32 v[2:3], v[200:201]
	global_load_dwordx2 v[200:201], v[246:247], off offset:2048
	v_mov_b32_e32 v135, v1
	v_mov_b32_e32 v172, v196
	s_movk_i32 s1, 0x3c0
	s_movk_i32 s96, 0x1518
	s_nop 0
	v_lshlrev_b32_e32 v130, 16, v4
	v_and_b32_e32 v4, 0xffff0000, v4
	s_nop 0
	v_lshlrev_b32_e32 v131, 16, v2
	v_and_b32_e32 v2, 0xffff0000, v2
	v_mul_f32_e32 v2, 0xbfb8aa3b, v2
	v_exp_f32_e32 v133, v2
	v_lshlrev_b32_e32 v2, 16, v5
	v_mul_f32_e32 v4, 0xbfb8aa3b, v4
	v_mul_f32_e32 v2, 0xbfb8aa3b, v2
	v_exp_f32_e32 v4, v4
	v_exp_f32_e32 v2, v2
	v_and_b32_e32 v5, 0xffff0000, v5
	v_mul_f32_e32 v130, 0xbfb8aa3b, v130
	v_mul_f32_e32 v5, 0xbfb8aa3b, v5
	v_exp_f32_e32 v130, v130
	v_exp_f32_e32 v5, v5
	v_mul_f32_e32 v131, 0xbfb8aa3b, v131
	v_add_f32_e32 v4, 1.0, v4
	v_add_f32_e32 v2, 1.0, v2
	v_exp_f32_e32 v132, v131
	v_rcp_f32_e32 v131, v4
	v_rcp_f32_e32 v4, v2
	v_lshlrev_b32_e32 v2, 16, v3
	v_and_b32_e32 v3, 0xffff0000, v3
	v_mul_f32_e32 v2, 0xbfb8aa3b, v2
	v_mul_f32_e32 v3, 0xbfb8aa3b, v3
	v_add_f32_e32 v130, 1.0, v130
	v_exp_f32_e32 v2, v2
	v_add_f32_e32 v5, 1.0, v5
	v_exp_f32_e32 v3, v3
	v_rcp_f32_e32 v130, v130
	v_rcp_f32_e32 v5, v5
	v_pk_add_f32 v[132:133], v[132:133], 1.0 op_sel_hi:[1,0]
	v_pk_add_f32 v[2:3], v[2:3], 1.0 op_sel_hi:[1,0]
	v_pk_mul_f32 v[130:131], v[130:131], v[132:133]
	v_pk_mul_f32 v[2:3], v[4:5], v[2:3]
	v_lshl_add_u64 v[132:133], v[140:141], 0, v[134:135]
	v_pk_mul_f32 v[4:5], v[160:161], v[2:3]
	v_pk_mul_f32 v[2:3], v[158:159], v[130:131]
	v_lshl_add_u64 v[130:131], v[138:139], 0, v[134:135]
	s_waitcnt vmcnt(23)
	v_mov_b64_e32 v[130:131], v[202:203]
	global_load_dwordx2 v[202:203], v[246:247], off offset:32
	s_nop 0
	s_waitcnt vmcnt(23)
	v_mov_b64_e32 v[132:133], v[204:205]
	global_load_dwordx2 v[204:205], v[246:247], off offset:2080
	s_nop 0
	v_lshlrev_b32_e32 v143, 16, v130
	v_and_b32_e32 v130, 0xffff0000, v130
	v_mul_f32_e32 v130, 0xbfb8aa3b, v130
	v_exp_f32_e32 v130, v130
	v_mul_f32_e32 v143, 0xbfb8aa3b, v143
	v_exp_f32_e32 v143, v143
	v_add_f32_e32 v130, 1.0, v130
	v_rcp_f32_e32 v145, v130
	s_nop 0
	v_and_b32_e32 v130, 0xffff0000, v132
	v_mul_f32_e32 v130, 0xbfb8aa3b, v130
	v_exp_f32_e32 v147, v130
	v_lshlrev_b32_e32 v130, 16, v131
	v_and_b32_e32 v131, 0xffff0000, v131
	v_mul_f32_e32 v130, 0xbfb8aa3b, v130
	v_mul_f32_e32 v131, 0xbfb8aa3b, v131
	v_exp_f32_e32 v130, v130
	v_exp_f32_e32 v131, v131
	v_add_f32_e32 v143, 1.0, v143
	v_rcp_f32_e32 v144, v143
	v_lshlrev_b32_e32 v143, 16, v132
	v_lshlrev_b32_e32 v132, 16, v133
	v_and_b32_e32 v133, 0xffff0000, v133
	v_mul_f32_e32 v132, 0xbfb8aa3b, v132
	v_mul_f32_e32 v133, 0xbfb8aa3b, v133
	v_add_f32_e32 v130, 1.0, v130
	v_exp_f32_e32 v132, v132
	v_add_f32_e32 v131, 1.0, v131
	v_exp_f32_e32 v133, v133
	v_rcp_f32_e32 v130, v130
	v_rcp_f32_e32 v131, v131
	v_mul_f32_e32 v143, 0xbfb8aa3b, v143
	v_pk_add_f32 v[132:133], v[132:133], 1.0 op_sel_hi:[1,0]
	v_exp_f32_e32 v146, v143
	v_pk_mul_f32 v[130:131], v[130:131], v[132:133]
	v_or_b32_e32 v132, 64, v0
	v_mov_b32_e32 v133, v1
	v_pk_mul_f32 v[8:9], v[8:9], v[130:131]
	v_lshl_add_u64 v[130:131], v[138:139], 0, v[132:133]
	s_waitcnt vmcnt(23)
	v_mov_b64_e32 v[130:131], v[206:207]
	global_load_dwordx2 v[206:207], v[246:247], off offset:64
	v_pk_add_f32 v[146:147], v[146:147], 1.0 op_sel_hi:[1,0]
	s_nop 0
	v_pk_mul_f32 v[144:145], v[144:145], v[146:147]
	s_nop 0
	v_pk_mul_f32 v[6:7], v[6:7], v[144:145]
	v_lshl_add_u64 v[144:145], v[140:141], 0, v[132:133]
	s_waitcnt vmcnt(23)
	v_mov_b64_e32 v[144:145], v[208:209]
	global_load_dwordx2 v[208:209], v[246:247], off offset:2112
	s_nop 0
	v_lshlrev_b32_e32 v143, 16, v130
	v_and_b32_e32 v130, 0xffff0000, v130
	v_mul_f32_e32 v130, 0xbfb8aa3b, v130
	v_exp_f32_e32 v130, v130
	v_mul_f32_e32 v143, 0xbfb8aa3b, v143
	v_exp_f32_e32 v143, v143
	v_add_f32_e32 v130, 1.0, v130
	v_rcp_f32_e32 v147, v130
	s_nop 0
	v_and_b32_e32 v130, 0xffff0000, v144
	v_add_f32_e32 v143, 1.0, v143
	v_mul_f32_e32 v130, 0xbfb8aa3b, v130
	v_rcp_f32_e32 v146, v143
	v_lshlrev_b32_e32 v143, 16, v144
	v_exp_f32_e32 v149, v130
	v_lshlrev_b32_e32 v130, 16, v131
	v_and_b32_e32 v131, 0xffff0000, v131
	v_mul_f32_e32 v143, 0xbfb8aa3b, v143
	v_mul_f32_e32 v130, 0xbfb8aa3b, v130
	v_mul_f32_e32 v131, 0xbfb8aa3b, v131
	v_exp_f32_e32 v148, v143
	v_exp_f32_e32 v130, v130
	v_lshlrev_b32_e32 v143, 16, v145
	v_exp_f32_e32 v131, v131
	v_mul_f32_e32 v143, 0xbfb8aa3b, v143
	v_exp_f32_e32 v144, v143
	v_and_b32_e32 v143, 0xffff0000, v145
	v_mul_f32_e32 v143, 0xbfb8aa3b, v143
	v_add_f32_e32 v130, 1.0, v130
	v_add_f32_e32 v131, 1.0, v131
	v_exp_f32_e32 v145, v143
	v_rcp_f32_e32 v130, v130
	v_rcp_f32_e32 v131, v131
	v_pk_add_f32 v[148:149], v[148:149], 1.0 op_sel_hi:[1,0]
	v_pk_add_f32 v[144:145], v[144:145], 1.0 op_sel_hi:[1,0]
	v_pk_mul_f32 v[146:147], v[146:147], v[148:149]
	v_pk_mul_f32 v[130:131], v[130:131], v[144:145]
	v_pk_mul_f32 v[10:11], v[10:11], v[146:147]
	v_pk_mul_f32 v[12:13], v[12:13], v[130:131]
	v_or_b32_e32 v130, 0x60, v0
	v_mov_b32_e32 v131, v1
	v_lshl_add_u64 v[138:139], v[138:139], 0, v[130:131]
	s_waitcnt vmcnt(23)
	v_mov_b64_e32 v[138:139], v[210:211]
	global_load_dwordx2 v[210:211], v[246:247], off offset:96
	v_lshl_add_u64 v[140:141], v[140:141], 0, v[130:131]
	s_waitcnt vmcnt(23)
; DI float bflo(unsigned u) { return __uint_as_float(u << 16); }
; DI float bfhi(unsigned u) { return __uint_as_float(u & 0xffff0000u); }
; DI float sigmoidf(float x) { return __builtin_amdgcn_rcpf(1.f + __expf(-x)); }
; DI float inv_sigmoidf(float x) { return 1.f + __expf(-x); }
; __global__ void __launch_bounds__(512, 2) mega(Params p) {
;     ...
;       gemm8_epi(acc8, m0, n0, [&](int m, int n, f32x4& a) {
;         uint2 ua = *(const uint2*)(z + (size_t)m * ZS + C_MA + n);
;         uint2 ub = *(const uint2*)(z + (size_t)m * ZS + C_MB + n);
;         a[0] *= sigmoidf(bflo(ua.x)) * inv_sigmoidf(bflo(ub.x));
;         a[1] *= sigmoidf(bfhi(ua.x)) * inv_sigmoidf(bfhi(ub.x));
;         a[2] *= sigmoidf(bflo(ua.y)) * inv_sigmoidf(bflo(ub.y));
;         a[3] *= sigmoidf(bfhi(ua.y)) * inv_sigmoidf(bfhi(ub.y));
;       });
	v_mov_b64_e32 v[140:141], v[212:213]
	global_load_dwordx2 v[212:213], v[246:247], off offset:2144
	s_nop 0
	v_lshlrev_b32_e32 v143, 16, v138
	v_and_b32_e32 v138, 0xffff0000, v138
	v_mul_f32_e32 v138, 0xbfb8aa3b, v138
	v_exp_f32_e32 v138, v138
	v_mul_f32_e32 v143, 0xbfb8aa3b, v143
	v_exp_f32_e32 v143, v143
	v_add_f32_e32 v138, 1.0, v138
	v_rcp_f32_e32 v145, v138
	s_nop 0
	v_and_b32_e32 v138, 0xffff0000, v140
	v_mul_f32_e32 v138, 0xbfb8aa3b, v138
	v_exp_f32_e32 v147, v138
	v_lshlrev_b32_e32 v138, 16, v139
	v_and_b32_e32 v139, 0xffff0000, v139
	v_mul_f32_e32 v138, 0xbfb8aa3b, v138
	v_mul_f32_e32 v139, 0xbfb8aa3b, v139
	v_exp_f32_e32 v138, v138
	v_exp_f32_e32 v139, v139
	v_add_f32_e32 v143, 1.0, v143
	v_rcp_f32_e32 v144, v143
	v_lshlrev_b32_e32 v143, 16, v140
	v_lshlrev_b32_e32 v140, 16, v141
	v_and_b32_e32 v141, 0xffff0000, v141
	v_mul_f32_e32 v140, 0xbfb8aa3b, v140
	v_mul_f32_e32 v141, 0xbfb8aa3b, v141
	v_add_f32_e32 v138, 1.0, v138
	v_exp_f32_e32 v140, v140
	v_add_f32_e32 v139, 1.0, v139
	v_exp_f32_e32 v141, v141
	v_rcp_f32_e32 v138, v138
	v_rcp_f32_e32 v139, v139
	v_mul_f32_e32 v143, 0xbfb8aa3b, v143
	v_exp_f32_e32 v146, v143
	v_pk_add_f32 v[140:141], v[140:141], 1.0 op_sel_hi:[1,0]
	v_pk_add_f32 v[146:147], v[146:147], 1.0 op_sel_hi:[1,0]
	v_pk_mul_f32 v[138:139], v[138:139], v[140:141]
	v_pk_mul_f32 v[144:145], v[144:145], v[146:147]
	v_pk_mul_f32 v[16:17], v[16:17], v[138:139]
	v_or_b32_e32 v138, 16, v142
	v_mad_i64_i32 v[140:141], s[26:27], v138, s35, v[136:137]
	v_lshl_add_u64 v[138:139], v[140:141], 0, s[30:31]
	v_pk_mul_f32 v[14:15], v[14:15], v[144:145]
	v_lshl_add_u64 v[144:145], v[138:139], 0, v[0:1]
	s_waitcnt vmcnt(23)
	v_mov_b64_e32 v[144:145], v[214:215]
	v_lshl_add_u64 v[246:247], v[246:247], 0, s[88:89]
	global_load_dwordx2 v[214:215], v[246:247], off
	v_lshl_add_u64 v[140:141], v[140:141], 0, s[42:43]
	v_lshl_add_u64 v[146:147], v[140:141], 0, v[0:1]
	s_waitcnt vmcnt(23)
	v_mov_b64_e32 v[146:147], v[216:217]
	global_load_dwordx2 v[216:217], v[246:247], off offset:2048
	s_nop 0
	v_lshlrev_b32_e32 v143, 16, v144
	v_mul_f32_e32 v143, 0xbfb8aa3b, v143
	v_exp_f32_e32 v143, v143
	s_nop 0
	v_add_f32_e32 v143, 1.0, v143
	v_rcp_f32_e32 v148, v143
	s_nop 0
	v_lshlrev_b32_e32 v143, 16, v146
	v_mul_f32_e32 v143, 0xbfb8aa3b, v143
	v_exp_f32_e32 v150, v143
	v_and_b32_e32 v143, 0xffff0000, v144
	v_mul_f32_e32 v143, 0xbfb8aa3b, v143
	v_exp_f32_e32 v143, v143
	s_nop 0
	v_add_f32_e32 v143, 1.0, v143
	v_rcp_f32_e32 v149, v143
	v_and_b32_e32 v143, 0xffff0000, v146
	v_mul_f32_e32 v143, 0xbfb8aa3b, v143
	v_exp_f32_e32 v151, v143
	v_lshlrev_b32_e32 v143, 16, v145
	v_mul_f32_e32 v143, 0xbfb8aa3b, v143
	v_exp_f32_e32 v143, v143
	v_pk_add_f32 v[150:151], v[150:151], 1.0 op_sel_hi:[1,0]
	v_add_f32_e32 v143, 1.0, v143
	v_rcp_f32_e32 v144, v143
	v_lshlrev_b32_e32 v143, 16, v147
	v_mul_f32_e32 v143, 0xbfb8aa3b, v143
	v_exp_f32_e32 v146, v143
	v_and_b32_e32 v143, 0xffff0000, v145
	v_mul_f32_e32 v143, 0xbfb8aa3b, v143
	v_exp_f32_e32 v143, v143
	v_pk_mul_f32 v[148:149], v[148:149], v[150:151]
	v_add_f32_e32 v143, 1.0, v143
	v_rcp_f32_e32 v145, v143
	v_and_b32_e32 v143, 0xffff0000, v147
	v_mul_f32_e32 v143, 0xbfb8aa3b, v143
	v_exp_f32_e32 v147, v143
	v_pk_mul_f32 v[22:23], v[22:23], v[148:149]
	v_pk_add_f32 v[146:147], v[146:147], 1.0 op_sel_hi:[1,0]
	s_nop 0
	v_pk_mul_f32 v[144:145], v[144:145], v[146:147]
	v_lshl_add_u64 v[146:147], v[140:141], 0, v[134:135]
	v_pk_mul_f32 v[24:25], v[24:25], v[144:145]
	v_lshl_add_u64 v[144:145], v[138:139], 0, v[134:135]
	s_waitcnt vmcnt(23)
	v_mov_b64_e32 v[144:145], v[218:219]
	global_load_dwordx2 v[218:219], v[246:247], off offset:32
	s_nop 0
	s_waitcnt vmcnt(23)
	v_mov_b64_e32 v[146:147], v[220:221]
	global_load_dwordx2 v[220:221], v[246:247], off offset:2080
	s_nop 0
	v_lshlrev_b32_e32 v143, 16, v144
	v_mul_f32_e32 v143, 0xbfb8aa3b, v143
	v_exp_f32_e32 v143, v143
	s_nop 0
	v_add_f32_e32 v143, 1.0, v143
	v_rcp_f32_e32 v148, v143
	s_nop 0
	v_lshlrev_b32_e32 v143, 16, v146
	v_mul_f32_e32 v143, 0xbfb8aa3b, v143
	v_exp_f32_e32 v150, v143
	v_and_b32_e32 v143, 0xffff0000, v144
	v_mul_f32_e32 v143, 0xbfb8aa3b, v143
	v_exp_f32_e32 v143, v143
	s_nop 0
	v_add_f32_e32 v143, 1.0, v143
	v_rcp_f32_e32 v149, v143
	v_and_b32_e32 v143, 0xffff0000, v146
	v_mul_f32_e32 v143, 0xbfb8aa3b, v143
	v_exp_f32_e32 v151, v143
	v_lshlrev_b32_e32 v143, 16, v145
	v_mul_f32_e32 v143, 0xbfb8aa3b, v143
	v_exp_f32_e32 v143, v143
	v_pk_add_f32 v[150:151], v[150:151], 1.0 op_sel_hi:[1,0]
	v_add_f32_e32 v143, 1.0, v143
	v_rcp_f32_e32 v144, v143
	v_lshlrev_b32_e32 v143, 16, v147
	v_mul_f32_e32 v143, 0xbfb8aa3b, v143
	v_exp_f32_e32 v146, v143
	v_and_b32_e32 v143, 0xffff0000, v145
	v_mul_f32_e32 v143, 0xbfb8aa3b, v143
	v_exp_f32_e32 v143, v143
	v_pk_mul_f32 v[148:149], v[148:149], v[150:151]
	v_add_f32_e32 v143, 1.0, v143
	v_rcp_f32_e32 v145, v143
	v_and_b32_e32 v143, 0xffff0000, v147
	v_mul_f32_e32 v143, 0xbfb8aa3b, v143
	v_exp_f32_e32 v147, v143
	v_pk_mul_f32 v[30:31], v[30:31], v[148:149]
	v_pk_add_f32 v[146:147], v[146:147], 1.0 op_sel_hi:[1,0]
	s_nop 0
	v_pk_mul_f32 v[144:145], v[144:145], v[146:147]
	v_lshl_add_u64 v[146:147], v[140:141], 0, v[132:133]
	v_pk_mul_f32 v[32:33], v[32:33], v[144:145]
	v_lshl_add_u64 v[144:145], v[138:139], 0, v[132:133]
	s_waitcnt vmcnt(23)
	v_mov_b64_e32 v[144:145], v[222:223]
	global_load_dwordx2 v[222:223], v[246:247], off offset:64
	v_lshl_add_u64 v[138:139], v[138:139], 0, v[130:131]
	s_waitcnt vmcnt(23)
	v_mov_b64_e32 v[146:147], v[224:225]
	global_load_dwordx2 v[224:225], v[246:247], off offset:2112
	v_lshl_add_u64 v[140:141], v[140:141], 0, v[130:131]
	s_waitcnt vmcnt(23)
; DI float bflo(unsigned u) { return __uint_as_float(u << 16); }
; DI float bfhi(unsigned u) { return __uint_as_float(u & 0xffff0000u); }
; DI float sigmoidf(float x) { return __builtin_amdgcn_rcpf(1.f + __expf(-x)); }
; DI float inv_sigmoidf(float x) { return 1.f + __expf(-x); }
; __global__ void __launch_bounds__(512, 2) mega(Params p) {
;     ...
;       gemm8_epi(acc8, m0, n0, [&](int m, int n, f32x4& a) {
;         uint2 ua = *(const uint2*)(z + (size_t)m * ZS + C_MA + n);
;         uint2 ub = *(const uint2*)(z + (size_t)m * ZS + C_MB + n);
;         a[0] *= sigmoidf(bflo(ua.x)) * inv_sigmoidf(bflo(ub.x));
;         a[1] *= sigmoidf(bfhi(ua.x)) * inv_sigmoidf(bfhi(ub.x));
;         a[2] *= sigmoidf(bflo(ua.y)) * inv_sigmoidf(bflo(ub.y));
;         a[3] *= sigmoidf(bfhi(ua.y)) * inv_sigmoidf(bfhi(ub.y));
;       });
	v_mov_b64_e32 v[138:139], v[226:227]
	global_load_dwordx2 v[226:227], v[246:247], off offset:96
	s_nop 0
	s_waitcnt vmcnt(23)
	v_mov_b64_e32 v[140:141], v[228:229]
	global_load_dwordx2 v[228:229], v[246:247], off offset:2144
	s_nop 0
	v_lshlrev_b32_e32 v143, 16, v144
	v_mul_f32_e32 v143, 0xbfb8aa3b, v143
	v_exp_f32_e32 v143, v143
	s_nop 0
	v_add_f32_e32 v143, 1.0, v143
	v_rcp_f32_e32 v148, v143
	s_nop 0
	v_lshlrev_b32_e32 v143, 16, v146
	v_mul_f32_e32 v143, 0xbfb8aa3b, v143
	v_exp_f32_e32 v150, v143
	v_and_b32_e32 v143, 0xffff0000, v144
	v_mul_f32_e32 v143, 0xbfb8aa3b, v143
	v_exp_f32_e32 v143, v143
	s_nop 0
	v_add_f32_e32 v143, 1.0, v143
	v_rcp_f32_e32 v149, v143
	v_and_b32_e32 v143, 0xffff0000, v146
	v_mul_f32_e32 v143, 0xbfb8aa3b, v143
	v_exp_f32_e32 v151, v143
	v_lshlrev_b32_e32 v143, 16, v145
	v_mul_f32_e32 v143, 0xbfb8aa3b, v143
	v_exp_f32_e32 v143, v143
	v_pk_add_f32 v[150:151], v[150:151], 1.0 op_sel_hi:[1,0]
	v_add_f32_e32 v143, 1.0, v143
	v_rcp_f32_e32 v144, v143
	v_lshlrev_b32_e32 v143, 16, v147
	v_mul_f32_e32 v143, 0xbfb8aa3b, v143
	v_exp_f32_e32 v146, v143
	v_and_b32_e32 v143, 0xffff0000, v145
	v_mul_f32_e32 v143, 0xbfb8aa3b, v143
	v_exp_f32_e32 v143, v143
	v_pk_mul_f32 v[148:149], v[148:149], v[150:151]
	v_add_f32_e32 v143, 1.0, v143
	v_rcp_f32_e32 v145, v143
	v_and_b32_e32 v143, 0xffff0000, v147
	v_mul_f32_e32 v143, 0xbfb8aa3b, v143
	v_exp_f32_e32 v147, v143
	s_nop 0
	v_lshlrev_b32_e32 v143, 16, v138
	v_and_b32_e32 v138, 0xffff0000, v138
	v_mul_f32_e32 v138, 0xbfb8aa3b, v138
	v_exp_f32_e32 v138, v138
	v_pk_add_f32 v[146:147], v[146:147], 1.0 op_sel_hi:[1,0]
	v_mul_f32_e32 v143, 0xbfb8aa3b, v143
	v_pk_mul_f32 v[144:145], v[144:145], v[146:147]
	v_add_f32_e32 v138, 1.0, v138
	v_pk_mul_f32 v[40:41], v[40:41], v[144:145]
	v_rcp_f32_e32 v145, v138
	s_nop 0
	v_and_b32_e32 v138, 0xffff0000, v140
	v_exp_f32_e32 v143, v143
	v_mul_f32_e32 v138, 0xbfb8aa3b, v138
	v_exp_f32_e32 v147, v138
	v_lshlrev_b32_e32 v138, 16, v139
	v_and_b32_e32 v139, 0xffff0000, v139
	v_mul_f32_e32 v138, 0xbfb8aa3b, v138
	v_mul_f32_e32 v139, 0xbfb8aa3b, v139
	v_exp_f32_e32 v138, v138
	v_exp_f32_e32 v139, v139
	v_add_f32_e32 v143, 1.0, v143
	v_rcp_f32_e32 v144, v143
	v_lshlrev_b32_e32 v143, 16, v140
	v_lshlrev_b32_e32 v140, 16, v141
	v_and_b32_e32 v141, 0xffff0000, v141
	v_mul_f32_e32 v140, 0xbfb8aa3b, v140
	v_mul_f32_e32 v141, 0xbfb8aa3b, v141
	v_add_f32_e32 v138, 1.0, v138
	v_exp_f32_e32 v140, v140
	v_add_f32_e32 v139, 1.0, v139
	v_exp_f32_e32 v141, v141
	v_rcp_f32_e32 v138, v138
	v_rcp_f32_e32 v139, v139
	v_mul_f32_e32 v143, 0xbfb8aa3b, v143
	v_exp_f32_e32 v146, v143
	v_pk_add_f32 v[140:141], v[140:141], 1.0 op_sel_hi:[1,0]
	v_pk_mul_f32 v[38:39], v[38:39], v[148:149]
	v_pk_mul_f32 v[138:139], v[138:139], v[140:141]
	v_pk_add_f32 v[146:147], v[146:147], 1.0 op_sel_hi:[1,0]
	v_pk_mul_f32 v[48:49], v[48:49], v[138:139]
	v_or_b32_e32 v138, 32, v142
	v_mad_i64_i32 v[140:141], s[26:27], v138, s35, v[136:137]
	v_pk_mul_f32 v[144:145], v[144:145], v[146:147]
	v_lshl_add_u64 v[138:139], v[140:141], 0, s[30:31]
	v_pk_mul_f32 v[46:47], v[46:47], v[144:145]
	v_lshl_add_u64 v[144:145], v[138:139], 0, v[0:1]
	s_waitcnt vmcnt(23)
	v_mov_b64_e32 v[144:145], v[230:231]
	v_lshl_add_u64 v[246:247], v[246:247], 0, s[88:89]
	global_load_dwordx2 v[230:231], v[246:247], off
	v_lshl_add_u64 v[140:141], v[140:141], 0, s[42:43]
	v_lshl_add_u64 v[146:147], v[140:141], 0, v[0:1]
	s_waitcnt vmcnt(23)
	v_mov_b64_e32 v[146:147], v[232:233]
	global_load_dwordx2 v[232:233], v[246:247], off offset:2048
	s_nop 0
	v_lshlrev_b32_e32 v143, 16, v144
	v_mul_f32_e32 v143, 0xbfb8aa3b, v143
	v_exp_f32_e32 v143, v143
	s_nop 0
	v_add_f32_e32 v143, 1.0, v143
	v_rcp_f32_e32 v148, v143
	s_nop 0
	v_lshlrev_b32_e32 v143, 16, v146
	v_mul_f32_e32 v143, 0xbfb8aa3b, v143
	v_exp_f32_e32 v150, v143
	v_and_b32_e32 v143, 0xffff0000, v144
	v_mul_f32_e32 v143, 0xbfb8aa3b, v143
	v_exp_f32_e32 v143, v143
	s_nop 0
	v_add_f32_e32 v143, 1.0, v143
	v_rcp_f32_e32 v149, v143
	v_and_b32_e32 v143, 0xffff0000, v146
	v_mul_f32_e32 v143, 0xbfb8aa3b, v143
	v_exp_f32_e32 v151, v143
	v_lshlrev_b32_e32 v143, 16, v145
	v_mul_f32_e32 v143, 0xbfb8aa3b, v143
	v_exp_f32_e32 v143, v143
	v_pk_add_f32 v[150:151], v[150:151], 1.0 op_sel_hi:[1,0]
	v_add_f32_e32 v143, 1.0, v143
	v_rcp_f32_e32 v144, v143
	v_lshlrev_b32_e32 v143, 16, v147
	v_mul_f32_e32 v143, 0xbfb8aa3b, v143
	v_exp_f32_e32 v146, v143
	v_and_b32_e32 v143, 0xffff0000, v145
	v_mul_f32_e32 v143, 0xbfb8aa3b, v143
	v_exp_f32_e32 v143, v143
	v_pk_mul_f32 v[148:149], v[148:149], v[150:151]
	v_add_f32_e32 v143, 1.0, v143
	v_rcp_f32_e32 v145, v143
	v_and_b32_e32 v143, 0xffff0000, v147
	v_mul_f32_e32 v143, 0xbfb8aa3b, v143
	v_exp_f32_e32 v147, v143
	v_pk_mul_f32 v[54:55], v[54:55], v[148:149]
	v_pk_add_f32 v[146:147], v[146:147], 1.0 op_sel_hi:[1,0]
	s_nop 0
	v_pk_mul_f32 v[144:145], v[144:145], v[146:147]
	v_lshl_add_u64 v[146:147], v[140:141], 0, v[134:135]
	v_pk_mul_f32 v[56:57], v[56:57], v[144:145]
	v_lshl_add_u64 v[144:145], v[138:139], 0, v[134:135]
	s_waitcnt vmcnt(23)
	v_mov_b64_e32 v[144:145], v[234:235]
	global_load_dwordx2 v[234:235], v[246:247], off offset:32
	s_nop 0
	s_waitcnt vmcnt(23)
; DI float bflo(unsigned u) { return __uint_as_float(u << 16); }
; DI float bfhi(unsigned u) { return __uint_as_float(u & 0xffff0000u); }
; DI float sigmoidf(float x) { return __builtin_amdgcn_rcpf(1.f + __expf(-x)); }
; DI float inv_sigmoidf(float x) { return 1.f + __expf(-x); }
; __global__ void __launch_bounds__(512, 2) mega(Params p) {
;     ...
;       gemm8_epi(acc8, m0, n0, [&](int m, int n, f32x4& a) {
;         uint2 ua = *(const uint2*)(z + (size_t)m * ZS + C_MA + n);
;         uint2 ub = *(const uint2*)(z + (size_t)m * ZS + C_MB + n);
;         a[0] *= sigmoidf(bflo(ua.x)) * inv_sigmoidf(bflo(ub.x));
;         a[1] *= sigmoidf(bfhi(ua.x)) * inv_sigmoidf(bfhi(ub.x));
;         a[2] *= sigmoidf(bflo(ua.y)) * inv_sigmoidf(bflo(ub.y));
;         a[3] *= sigmoidf(bfhi(ua.y)) * inv_sigmoidf(bfhi(ub.y));
;       });
	v_mov_b64_e32 v[146:147], v[236:237]
	global_load_dwordx2 v[236:237], v[246:247], off offset:2080
	s_nop 0
	v_lshlrev_b32_e32 v143, 16, v144
	v_mul_f32_e32 v143, 0xbfb8aa3b, v143
	v_exp_f32_e32 v143, v143
	s_nop 0
	v_add_f32_e32 v143, 1.0, v143
	v_rcp_f32_e32 v148, v143
	s_nop 0
	v_lshlrev_b32_e32 v143, 16, v146
	v_mul_f32_e32 v143, 0xbfb8aa3b, v143
	v_exp_f32_e32 v150, v143
	v_and_b32_e32 v143, 0xffff0000, v144
	v_mul_f32_e32 v143, 0xbfb8aa3b, v143
	v_exp_f32_e32 v143, v143
	s_nop 0
	v_add_f32_e32 v143, 1.0, v143
	v_rcp_f32_e32 v149, v143
	v_and_b32_e32 v143, 0xffff0000, v146
	v_mul_f32_e32 v143, 0xbfb8aa3b, v143
	v_exp_f32_e32 v151, v143
	v_lshlrev_b32_e32 v143, 16, v145
	v_mul_f32_e32 v143, 0xbfb8aa3b, v143
	v_exp_f32_e32 v143, v143
	v_pk_add_f32 v[150:151], v[150:151], 1.0 op_sel_hi:[1,0]
	v_add_f32_e32 v143, 1.0, v143
	v_rcp_f32_e32 v144, v143
	v_lshlrev_b32_e32 v143, 16, v147
	v_mul_f32_e32 v143, 0xbfb8aa3b, v143
	v_exp_f32_e32 v146, v143
	v_and_b32_e32 v143, 0xffff0000, v145
	v_mul_f32_e32 v143, 0xbfb8aa3b, v143
	v_exp_f32_e32 v143, v143
	v_pk_mul_f32 v[148:149], v[148:149], v[150:151]
	v_add_f32_e32 v143, 1.0, v143
	v_rcp_f32_e32 v145, v143
	v_and_b32_e32 v143, 0xffff0000, v147
	v_mul_f32_e32 v143, 0xbfb8aa3b, v143
	v_exp_f32_e32 v147, v143
	v_pk_mul_f32 v[62:63], v[62:63], v[148:149]
	v_pk_add_f32 v[146:147], v[146:147], 1.0 op_sel_hi:[1,0]
	s_nop 0
	v_pk_mul_f32 v[144:145], v[144:145], v[146:147]
	v_lshl_add_u64 v[146:147], v[140:141], 0, v[132:133]
	v_pk_mul_f32 v[64:65], v[64:65], v[144:145]
	v_lshl_add_u64 v[144:145], v[138:139], 0, v[132:133]
	s_waitcnt vmcnt(23)
	v_mov_b64_e32 v[144:145], v[238:239]
	global_load_dwordx2 v[238:239], v[246:247], off offset:64
	v_lshl_add_u64 v[138:139], v[138:139], 0, v[130:131]
	s_waitcnt vmcnt(23)
	v_mov_b64_e32 v[146:147], v[240:241]
	global_load_dwordx2 v[240:241], v[246:247], off offset:2112
	v_lshl_add_u64 v[140:141], v[140:141], 0, v[130:131]
	s_waitcnt vmcnt(23)
	v_mov_b64_e32 v[138:139], v[242:243]
	global_load_dwordx2 v[242:243], v[246:247], off offset:96
	s_nop 0
	s_waitcnt vmcnt(23)
	v_mov_b64_e32 v[140:141], v[244:245]
	global_load_dwordx2 v[244:245], v[246:247], off offset:2144
	s_nop 0
	v_lshlrev_b32_e32 v143, 16, v144
	v_mul_f32_e32 v143, 0xbfb8aa3b, v143
	v_exp_f32_e32 v143, v143
	s_nop 0
	v_add_f32_e32 v143, 1.0, v143
	v_rcp_f32_e32 v148, v143
	s_nop 0
	v_lshlrev_b32_e32 v143, 16, v146
	v_mul_f32_e32 v143, 0xbfb8aa3b, v143
	v_exp_f32_e32 v150, v143
	v_and_b32_e32 v143, 0xffff0000, v144
	v_mul_f32_e32 v143, 0xbfb8aa3b, v143
	v_exp_f32_e32 v143, v143
	s_nop 0
	v_add_f32_e32 v143, 1.0, v143
	v_rcp_f32_e32 v149, v143
	v_and_b32_e32 v143, 0xffff0000, v146
	v_mul_f32_e32 v143, 0xbfb8aa3b, v143
	v_exp_f32_e32 v151, v143
	v_lshlrev_b32_e32 v143, 16, v145
	v_mul_f32_e32 v143, 0xbfb8aa3b, v143
	v_exp_f32_e32 v143, v143
	v_pk_add_f32 v[150:151], v[150:151], 1.0 op_sel_hi:[1,0]
	v_add_f32_e32 v143, 1.0, v143
	v_rcp_f32_e32 v144, v143
	v_lshlrev_b32_e32 v143, 16, v147
	v_mul_f32_e32 v143, 0xbfb8aa3b, v143
	v_exp_f32_e32 v146, v143
	v_and_b32_e32 v143, 0xffff0000, v145
	v_mul_f32_e32 v143, 0xbfb8aa3b, v143
	v_exp_f32_e32 v143, v143
	v_pk_mul_f32 v[148:149], v[148:149], v[150:151]
	v_add_f32_e32 v143, 1.0, v143
	v_rcp_f32_e32 v145, v143
	v_and_b32_e32 v143, 0xffff0000, v147
	v_mul_f32_e32 v143, 0xbfb8aa3b, v143
	v_exp_f32_e32 v147, v143
	s_nop 0
	v_lshlrev_b32_e32 v143, 16, v138
	v_and_b32_e32 v138, 0xffff0000, v138
	v_mul_f32_e32 v138, 0xbfb8aa3b, v138
	v_exp_f32_e32 v138, v138
	v_pk_add_f32 v[146:147], v[146:147], 1.0 op_sel_hi:[1,0]
	v_mul_f32_e32 v143, 0xbfb8aa3b, v143
	v_pk_mul_f32 v[144:145], v[144:145], v[146:147]
	v_add_f32_e32 v138, 1.0, v138
	v_pk_mul_f32 v[72:73], v[72:73], v[144:145]
	v_rcp_f32_e32 v145, v138
	s_nop 0
	v_and_b32_e32 v138, 0xffff0000, v140
	v_exp_f32_e32 v143, v143
	v_mul_f32_e32 v138, 0xbfb8aa3b, v138
	v_exp_f32_e32 v147, v138
	v_lshlrev_b32_e32 v138, 16, v139
	v_and_b32_e32 v139, 0xffff0000, v139
	v_mul_f32_e32 v138, 0xbfb8aa3b, v138
	v_mul_f32_e32 v139, 0xbfb8aa3b, v139
	v_exp_f32_e32 v138, v138
	v_exp_f32_e32 v139, v139
	v_add_f32_e32 v143, 1.0, v143
	v_rcp_f32_e32 v144, v143
	v_lshlrev_b32_e32 v143, 16, v140
	v_lshlrev_b32_e32 v140, 16, v141
	v_and_b32_e32 v141, 0xffff0000, v141
	v_mul_f32_e32 v140, 0xbfb8aa3b, v140
	v_mul_f32_e32 v141, 0xbfb8aa3b, v141
	v_add_f32_e32 v138, 1.0, v138
	v_exp_f32_e32 v140, v140
	v_add_f32_e32 v139, 1.0, v139
	v_exp_f32_e32 v141, v141
	v_rcp_f32_e32 v138, v138
	v_rcp_f32_e32 v139, v139
	v_mul_f32_e32 v143, 0xbfb8aa3b, v143
	v_exp_f32_e32 v146, v143
	v_pk_add_f32 v[140:141], v[140:141], 1.0 op_sel_hi:[1,0]
	v_pk_mul_f32 v[70:71], v[70:71], v[148:149]
	v_pk_mul_f32 v[138:139], v[138:139], v[140:141]
	v_pk_add_f32 v[146:147], v[146:147], 1.0 op_sel_hi:[1,0]
	v_pk_mul_f32 v[80:81], v[80:81], v[138:139]
	v_or_b32_e32 v138, 48, v142
	v_mad_i64_i32 v[140:141], s[26:27], v138, s35, v[136:137]
	v_pk_mul_f32 v[144:145], v[144:145], v[146:147]
	v_lshl_add_u64 v[138:139], v[140:141], 0, s[30:31]
	v_pk_mul_f32 v[78:79], v[78:79], v[144:145]
	v_lshl_add_u64 v[144:145], v[138:139], 0, v[0:1]
	s_waitcnt vmcnt(23)
	v_mov_b64_e32 v[144:145], v[198:199]
	v_lshl_add_u64 v[246:247], v[246:247], 0, s[88:89]
	global_load_dwordx2 v[198:199], v[246:247], off
	v_lshl_add_u64 v[140:141], v[140:141], 0, s[42:43]
	v_lshl_add_u64 v[146:147], v[140:141], 0, v[0:1]
	s_waitcnt vmcnt(23)
; DI float bflo(unsigned u) { return __uint_as_float(u << 16); }
; DI float bfhi(unsigned u) { return __uint_as_float(u & 0xffff0000u); }
; DI float sigmoidf(float x) { return __builtin_amdgcn_rcpf(1.f + __expf(-x)); }
; DI float inv_sigmoidf(float x) { return 1.f + __expf(-x); }
; __global__ void __launch_bounds__(512, 2) mega(Params p) {
;     ...
;       gemm8_epi(acc8, m0, n0, [&](int m, int n, f32x4& a) {
;         uint2 ua = *(const uint2*)(z + (size_t)m * ZS + C_MA + n);
;         uint2 ub = *(const uint2*)(z + (size_t)m * ZS + C_MB + n);
;         a[0] *= sigmoidf(bflo(ua.x)) * inv_sigmoidf(bflo(ub.x));
;         a[1] *= sigmoidf(bfhi(ua.x)) * inv_sigmoidf(bfhi(ub.x));
;         a[2] *= sigmoidf(bflo(ua.y)) * inv_sigmoidf(bflo(ub.y));
;         a[3] *= sigmoidf(bfhi(ua.y)) * inv_sigmoidf(bfhi(ub.y));
;       });
	v_mov_b64_e32 v[146:147], v[200:201]
	global_load_dwordx2 v[200:201], v[246:247], off offset:2048
	s_nop 0
	v_lshlrev_b32_e32 v143, 16, v144
	v_mul_f32_e32 v143, 0xbfb8aa3b, v143
	v_exp_f32_e32 v143, v143
	s_nop 0
	v_add_f32_e32 v143, 1.0, v143
	v_rcp_f32_e32 v148, v143
	s_nop 0
	v_lshlrev_b32_e32 v143, 16, v146
	v_mul_f32_e32 v143, 0xbfb8aa3b, v143
	v_exp_f32_e32 v150, v143
	v_and_b32_e32 v143, 0xffff0000, v144
	v_mul_f32_e32 v143, 0xbfb8aa3b, v143
	v_exp_f32_e32 v143, v143
	s_nop 0
	v_add_f32_e32 v143, 1.0, v143
	v_rcp_f32_e32 v149, v143
	v_and_b32_e32 v143, 0xffff0000, v146
	v_mul_f32_e32 v143, 0xbfb8aa3b, v143
	v_exp_f32_e32 v151, v143
	v_lshlrev_b32_e32 v143, 16, v145
	v_mul_f32_e32 v143, 0xbfb8aa3b, v143
	v_exp_f32_e32 v143, v143
	v_pk_add_f32 v[150:151], v[150:151], 1.0 op_sel_hi:[1,0]
	v_add_f32_e32 v143, 1.0, v143
	v_rcp_f32_e32 v144, v143
	v_lshlrev_b32_e32 v143, 16, v147
	v_mul_f32_e32 v143, 0xbfb8aa3b, v143
	v_exp_f32_e32 v146, v143
	v_and_b32_e32 v143, 0xffff0000, v145
	v_mul_f32_e32 v143, 0xbfb8aa3b, v143
	v_exp_f32_e32 v143, v143
	v_pk_mul_f32 v[148:149], v[148:149], v[150:151]
	v_add_f32_e32 v143, 1.0, v143
	v_rcp_f32_e32 v145, v143
	v_and_b32_e32 v143, 0xffff0000, v147
	v_mul_f32_e32 v143, 0xbfb8aa3b, v143
	v_exp_f32_e32 v147, v143
	v_pk_mul_f32 v[86:87], v[86:87], v[148:149]
	v_pk_add_f32 v[146:147], v[146:147], 1.0 op_sel_hi:[1,0]
	s_nop 0
	v_pk_mul_f32 v[144:145], v[144:145], v[146:147]
	v_lshl_add_u64 v[146:147], v[140:141], 0, v[134:135]
	v_pk_mul_f32 v[88:89], v[88:89], v[144:145]
	v_lshl_add_u64 v[144:145], v[138:139], 0, v[134:135]
	s_waitcnt vmcnt(23)
	v_mov_b64_e32 v[144:145], v[202:203]
	global_load_dwordx2 v[202:203], v[246:247], off offset:32
	s_nop 0
	s_waitcnt vmcnt(23)
	v_mov_b64_e32 v[146:147], v[204:205]
	global_load_dwordx2 v[204:205], v[246:247], off offset:2080
	s_nop 0
	v_lshlrev_b32_e32 v143, 16, v144
	v_mul_f32_e32 v143, 0xbfb8aa3b, v143
	v_exp_f32_e32 v143, v143
	s_nop 0
	v_add_f32_e32 v143, 1.0, v143
	v_rcp_f32_e32 v148, v143
	s_nop 0
	v_lshlrev_b32_e32 v143, 16, v146
	v_mul_f32_e32 v143, 0xbfb8aa3b, v143
	v_exp_f32_e32 v150, v143
	v_and_b32_e32 v143, 0xffff0000, v144
	v_mul_f32_e32 v143, 0xbfb8aa3b, v143
	v_exp_f32_e32 v143, v143
	s_nop 0
	v_add_f32_e32 v143, 1.0, v143
	v_rcp_f32_e32 v149, v143
	v_and_b32_e32 v143, 0xffff0000, v146
	v_mul_f32_e32 v143, 0xbfb8aa3b, v143
	v_exp_f32_e32 v151, v143
	v_lshlrev_b32_e32 v143, 16, v145
	v_mul_f32_e32 v143, 0xbfb8aa3b, v143
	v_exp_f32_e32 v143, v143
	v_pk_add_f32 v[150:151], v[150:151], 1.0 op_sel_hi:[1,0]
	v_add_f32_e32 v143, 1.0, v143
	v_rcp_f32_e32 v144, v143
	v_lshlrev_b32_e32 v143, 16, v147
	v_mul_f32_e32 v143, 0xbfb8aa3b, v143
	v_exp_f32_e32 v146, v143
	v_and_b32_e32 v143, 0xffff0000, v145
	v_mul_f32_e32 v143, 0xbfb8aa3b, v143
	v_exp_f32_e32 v143, v143
	v_pk_mul_f32 v[148:149], v[148:149], v[150:151]
	v_add_f32_e32 v143, 1.0, v143
	v_rcp_f32_e32 v145, v143
	v_and_b32_e32 v143, 0xffff0000, v147
	v_mul_f32_e32 v143, 0xbfb8aa3b, v143
	v_exp_f32_e32 v147, v143
	v_pk_mul_f32 v[94:95], v[94:95], v[148:149]
	v_pk_add_f32 v[146:147], v[146:147], 1.0 op_sel_hi:[1,0]
	s_nop 0
	v_pk_mul_f32 v[144:145], v[144:145], v[146:147]
	v_lshl_add_u64 v[146:147], v[140:141], 0, v[132:133]
	v_pk_mul_f32 v[96:97], v[96:97], v[144:145]
	v_lshl_add_u64 v[144:145], v[138:139], 0, v[132:133]
	s_waitcnt vmcnt(23)
	v_mov_b64_e32 v[144:145], v[206:207]
	global_load_dwordx2 v[206:207], v[246:247], off offset:64
	v_lshl_add_u64 v[138:139], v[138:139], 0, v[130:131]
	s_waitcnt vmcnt(23)
	v_mov_b64_e32 v[146:147], v[208:209]
	global_load_dwordx2 v[208:209], v[246:247], off offset:2112
	v_lshl_add_u64 v[140:141], v[140:141], 0, v[130:131]
	s_waitcnt vmcnt(23)
	v_mov_b64_e32 v[138:139], v[210:211]
	global_load_dwordx2 v[210:211], v[246:247], off offset:96
	s_nop 0
	s_waitcnt vmcnt(23)
	v_mov_b64_e32 v[140:141], v[212:213]
	global_load_dwordx2 v[212:213], v[246:247], off offset:2144
	s_nop 0
	v_lshlrev_b32_e32 v143, 16, v144
	v_mul_f32_e32 v143, 0xbfb8aa3b, v143
	v_exp_f32_e32 v143, v143
	s_nop 0
	v_add_f32_e32 v143, 1.0, v143
	v_rcp_f32_e32 v148, v143
	s_nop 0
	v_lshlrev_b32_e32 v143, 16, v146
	v_mul_f32_e32 v143, 0xbfb8aa3b, v143
	v_exp_f32_e32 v150, v143
	v_and_b32_e32 v143, 0xffff0000, v144
	v_mul_f32_e32 v143, 0xbfb8aa3b, v143
	v_exp_f32_e32 v143, v143
	s_nop 0
	v_add_f32_e32 v143, 1.0, v143
	v_rcp_f32_e32 v149, v143
	v_and_b32_e32 v143, 0xffff0000, v146
	v_mul_f32_e32 v143, 0xbfb8aa3b, v143
	v_exp_f32_e32 v151, v143
	v_lshlrev_b32_e32 v143, 16, v145
	v_mul_f32_e32 v143, 0xbfb8aa3b, v143
	v_exp_f32_e32 v143, v143
	v_pk_add_f32 v[150:151], v[150:151], 1.0 op_sel_hi:[1,0]
	v_add_f32_e32 v143, 1.0, v143
	v_rcp_f32_e32 v144, v143
	v_lshlrev_b32_e32 v143, 16, v147
	v_mul_f32_e32 v143, 0xbfb8aa3b, v143
	v_exp_f32_e32 v146, v143
	v_and_b32_e32 v143, 0xffff0000, v145
	v_mul_f32_e32 v143, 0xbfb8aa3b, v143
	v_exp_f32_e32 v143, v143
	v_pk_mul_f32 v[148:149], v[148:149], v[150:151]
	v_add_f32_e32 v143, 1.0, v143
	v_rcp_f32_e32 v145, v143
	v_and_b32_e32 v143, 0xffff0000, v147
	v_mul_f32_e32 v143, 0xbfb8aa3b, v143
	v_exp_f32_e32 v147, v143
	s_nop 0
	v_lshlrev_b32_e32 v143, 16, v138
	v_and_b32_e32 v138, 0xffff0000, v138
	v_mul_f32_e32 v138, 0xbfb8aa3b, v138
	v_exp_f32_e32 v138, v138
	v_pk_add_f32 v[146:147], v[146:147], 1.0 op_sel_hi:[1,0]
	v_mul_f32_e32 v143, 0xbfb8aa3b, v143
	v_pk_mul_f32 v[144:145], v[144:145], v[146:147]
	v_add_f32_e32 v138, 1.0, v138
	v_pk_mul_f32 v[104:105], v[104:105], v[144:145]
	v_rcp_f32_e32 v145, v138
	s_nop 0
	v_and_b32_e32 v138, 0xffff0000, v140
	v_exp_f32_e32 v143, v143
	v_mul_f32_e32 v138, 0xbfb8aa3b, v138
	v_exp_f32_e32 v147, v138
	v_lshlrev_b32_e32 v138, 16, v139
	v_and_b32_e32 v139, 0xffff0000, v139
	v_mul_f32_e32 v138, 0xbfb8aa3b, v138
	v_mul_f32_e32 v139, 0xbfb8aa3b, v139
	v_exp_f32_e32 v138, v138
	v_exp_f32_e32 v139, v139
	v_add_f32_e32 v143, 1.0, v143
	v_rcp_f32_e32 v144, v143
	v_lshlrev_b32_e32 v143, 16, v140
	v_lshlrev_b32_e32 v140, 16, v141
	v_and_b32_e32 v141, 0xffff0000, v141
	v_mul_f32_e32 v140, 0xbfb8aa3b, v140
	v_mul_f32_e32 v141, 0xbfb8aa3b, v141
	v_add_f32_e32 v138, 1.0, v138
	v_exp_f32_e32 v140, v140
	v_add_f32_e32 v139, 1.0, v139
	v_exp_f32_e32 v141, v141
	v_rcp_f32_e32 v138, v138
	v_rcp_f32_e32 v139, v139
	v_mul_f32_e32 v143, 0xbfb8aa3b, v143
	v_exp_f32_e32 v146, v143
	v_pk_add_f32 v[140:141], v[140:141], 1.0 op_sel_hi:[1,0]
	v_pk_mul_f32 v[102:103], v[102:103], v[148:149]
	v_pk_mul_f32 v[138:139], v[138:139], v[140:141]
	v_pk_add_f32 v[146:147], v[146:147], 1.0 op_sel_hi:[1,0]
	v_pk_mul_f32 v[112:113], v[112:113], v[138:139]
	v_or_b32_e32 v138, 64, v142
	v_mad_i64_i32 v[140:141], s[26:27], v138, s35, v[136:137]
	v_pk_mul_f32 v[144:145], v[144:145], v[146:147]
	v_lshl_add_u64 v[138:139], v[140:141], 0, s[30:31]
	v_pk_mul_f32 v[110:111], v[110:111], v[144:145]
	v_lshl_add_u64 v[144:145], v[138:139], 0, v[0:1]
	s_waitcnt vmcnt(23)
; DI float bflo(unsigned u) { return __uint_as_float(u << 16); }
; DI float bfhi(unsigned u) { return __uint_as_float(u & 0xffff0000u); }
; DI float sigmoidf(float x) { return __builtin_amdgcn_rcpf(1.f + __expf(-x)); }
; DI float inv_sigmoidf(float x) { return 1.f + __expf(-x); }
; __global__ void __launch_bounds__(512, 2) mega(Params p) {
;     ...
;       gemm8_epi(acc8, m0, n0, [&](int m, int n, f32x4& a) {
;         uint2 ua = *(const uint2*)(z + (size_t)m * ZS + C_MA + n);
;         uint2 ub = *(const uint2*)(z + (size_t)m * ZS + C_MB + n);
;         a[0] *= sigmoidf(bflo(ua.x)) * inv_sigmoidf(bflo(ub.x));
;         a[1] *= sigmoidf(bfhi(ua.x)) * inv_sigmoidf(bfhi(ub.x));
;         a[2] *= sigmoidf(bflo(ua.y)) * inv_sigmoidf(bflo(ub.y));
;         a[3] *= sigmoidf(bfhi(ua.y)) * inv_sigmoidf(bfhi(ub.y));
;       });
	v_mov_b64_e32 v[144:145], v[214:215]
	v_lshl_add_u64 v[246:247], v[246:247], 0, s[88:89]
	global_load_dwordx2 v[214:215], v[246:247], off
	v_lshl_add_u64 v[140:141], v[140:141], 0, s[42:43]
	v_lshl_add_u64 v[146:147], v[140:141], 0, v[0:1]
	s_waitcnt vmcnt(23)
	v_mov_b64_e32 v[146:147], v[216:217]
	global_load_dwordx2 v[216:217], v[246:247], off offset:2048
	s_nop 0
	v_lshlrev_b32_e32 v143, 16, v144
	v_mul_f32_e32 v143, 0xbfb8aa3b, v143
	v_exp_f32_e32 v143, v143
	s_nop 0
	v_add_f32_e32 v143, 1.0, v143
	v_rcp_f32_e32 v148, v143
	s_nop 0
	v_lshlrev_b32_e32 v143, 16, v146
	v_mul_f32_e32 v143, 0xbfb8aa3b, v143
	v_exp_f32_e32 v150, v143
	v_and_b32_e32 v143, 0xffff0000, v144
	v_mul_f32_e32 v143, 0xbfb8aa3b, v143
	v_exp_f32_e32 v143, v143
	s_nop 0
	v_add_f32_e32 v143, 1.0, v143
	v_rcp_f32_e32 v149, v143
	v_and_b32_e32 v143, 0xffff0000, v146
	v_mul_f32_e32 v143, 0xbfb8aa3b, v143
	v_exp_f32_e32 v151, v143
	v_lshlrev_b32_e32 v143, 16, v145
	v_mul_f32_e32 v143, 0xbfb8aa3b, v143
	v_exp_f32_e32 v143, v143
	v_pk_add_f32 v[150:151], v[150:151], 1.0 op_sel_hi:[1,0]
	v_add_f32_e32 v143, 1.0, v143
	v_rcp_f32_e32 v144, v143
	v_lshlrev_b32_e32 v143, 16, v147
	v_mul_f32_e32 v143, 0xbfb8aa3b, v143
	v_exp_f32_e32 v146, v143
	v_and_b32_e32 v143, 0xffff0000, v145
	v_mul_f32_e32 v143, 0xbfb8aa3b, v143
	v_exp_f32_e32 v143, v143
	v_pk_mul_f32 v[148:149], v[148:149], v[150:151]
	v_add_f32_e32 v143, 1.0, v143
	v_rcp_f32_e32 v145, v143
	v_and_b32_e32 v143, 0xffff0000, v147
	v_mul_f32_e32 v143, 0xbfb8aa3b, v143
	v_exp_f32_e32 v147, v143
	v_pk_mul_f32 v[118:119], v[118:119], v[148:149]
	v_pk_add_f32 v[146:147], v[146:147], 1.0 op_sel_hi:[1,0]
	s_nop 0
	v_pk_mul_f32 v[144:145], v[144:145], v[146:147]
	v_lshl_add_u64 v[146:147], v[140:141], 0, v[134:135]
	v_pk_mul_f32 v[120:121], v[120:121], v[144:145]
	v_lshl_add_u64 v[144:145], v[138:139], 0, v[134:135]
	s_waitcnt vmcnt(23)
	v_mov_b64_e32 v[144:145], v[218:219]
	global_load_dwordx2 v[218:219], v[246:247], off offset:32
	s_nop 0
	s_waitcnt vmcnt(23)
	v_mov_b64_e32 v[146:147], v[220:221]
	global_load_dwordx2 v[220:221], v[246:247], off offset:2080
	s_nop 0
	v_lshlrev_b32_e32 v143, 16, v144
	v_mul_f32_e32 v143, 0xbfb8aa3b, v143
	v_exp_f32_e32 v143, v143
	s_nop 0
	v_add_f32_e32 v143, 1.0, v143
	v_rcp_f32_e32 v148, v143
	s_nop 0
	v_lshlrev_b32_e32 v143, 16, v146
	v_mul_f32_e32 v143, 0xbfb8aa3b, v143
	v_exp_f32_e32 v150, v143
	v_and_b32_e32 v143, 0xffff0000, v144
	v_mul_f32_e32 v143, 0xbfb8aa3b, v143
	v_exp_f32_e32 v143, v143
	s_nop 0
	v_add_f32_e32 v143, 1.0, v143
	v_rcp_f32_e32 v149, v143
	v_and_b32_e32 v143, 0xffff0000, v146
	v_mul_f32_e32 v143, 0xbfb8aa3b, v143
	v_exp_f32_e32 v151, v143
	v_lshlrev_b32_e32 v143, 16, v145
	v_mul_f32_e32 v143, 0xbfb8aa3b, v143
	v_exp_f32_e32 v143, v143
	v_pk_add_f32 v[150:151], v[150:151], 1.0 op_sel_hi:[1,0]
	v_add_f32_e32 v143, 1.0, v143
	v_rcp_f32_e32 v144, v143
	v_lshlrev_b32_e32 v143, 16, v147
	v_mul_f32_e32 v143, 0xbfb8aa3b, v143
	v_exp_f32_e32 v146, v143
	v_and_b32_e32 v143, 0xffff0000, v145
	v_mul_f32_e32 v143, 0xbfb8aa3b, v143
	v_exp_f32_e32 v143, v143
	v_pk_mul_f32 v[148:149], v[148:149], v[150:151]
	v_add_f32_e32 v143, 1.0, v143
	v_rcp_f32_e32 v145, v143
	v_and_b32_e32 v143, 0xffff0000, v147
	v_mul_f32_e32 v143, 0xbfb8aa3b, v143
	v_exp_f32_e32 v147, v143
	v_pk_mul_f32 v[126:127], v[126:127], v[148:149]
	v_pk_add_f32 v[146:147], v[146:147], 1.0 op_sel_hi:[1,0]
	s_nop 0
	v_pk_mul_f32 v[144:145], v[144:145], v[146:147]
	v_lshl_add_u64 v[146:147], v[140:141], 0, v[132:133]
	v_pk_mul_f32 v[128:129], v[128:129], v[144:145]
	v_lshl_add_u64 v[144:145], v[138:139], 0, v[132:133]
	s_waitcnt vmcnt(23)
	v_mov_b64_e32 v[144:145], v[222:223]
	global_load_dwordx2 v[222:223], v[246:247], off offset:64
	v_lshl_add_u64 v[138:139], v[138:139], 0, v[130:131]
	s_waitcnt vmcnt(23)
	v_mov_b64_e32 v[146:147], v[224:225]
	global_load_dwordx2 v[224:225], v[246:247], off offset:2112
	v_lshl_add_u64 v[140:141], v[140:141], 0, v[130:131]
	s_waitcnt vmcnt(23)
	v_mov_b64_e32 v[138:139], v[226:227]
	global_load_dwordx2 v[226:227], v[246:247], off offset:96
	s_nop 0
	s_waitcnt vmcnt(23)
	v_mov_b64_e32 v[140:141], v[228:229]
	global_load_dwordx2 v[228:229], v[246:247], off offset:2144
	s_nop 0
	v_lshlrev_b32_e32 v143, 16, v144
	v_mul_f32_e32 v143, 0xbfb8aa3b, v143
	v_exp_f32_e32 v143, v143
	s_nop 0
	v_add_f32_e32 v143, 1.0, v143
	v_rcp_f32_e32 v148, v143
	s_nop 0
	v_lshlrev_b32_e32 v143, 16, v146
	v_mul_f32_e32 v143, 0xbfb8aa3b, v143
	v_exp_f32_e32 v150, v143
	v_and_b32_e32 v143, 0xffff0000, v144
	v_mul_f32_e32 v143, 0xbfb8aa3b, v143
	v_exp_f32_e32 v143, v143
	s_nop 0
	v_add_f32_e32 v143, 1.0, v143
	v_rcp_f32_e32 v149, v143
	v_and_b32_e32 v143, 0xffff0000, v146
	v_mul_f32_e32 v143, 0xbfb8aa3b, v143
	v_exp_f32_e32 v151, v143
	v_lshlrev_b32_e32 v143, 16, v145
	v_mul_f32_e32 v143, 0xbfb8aa3b, v143
	v_exp_f32_e32 v143, v143
	v_pk_add_f32 v[150:151], v[150:151], 1.0 op_sel_hi:[1,0]
	v_add_f32_e32 v143, 1.0, v143
	v_rcp_f32_e32 v144, v143
	v_lshlrev_b32_e32 v143, 16, v147
	v_mul_f32_e32 v143, 0xbfb8aa3b, v143
	v_exp_f32_e32 v146, v143
	v_and_b32_e32 v143, 0xffff0000, v145
	v_mul_f32_e32 v143, 0xbfb8aa3b, v143
	v_exp_f32_e32 v143, v143
	v_pk_mul_f32 v[148:149], v[148:149], v[150:151]
	v_add_f32_e32 v143, 1.0, v143
	v_rcp_f32_e32 v145, v143
	v_and_b32_e32 v143, 0xffff0000, v147
	v_mul_f32_e32 v143, 0xbfb8aa3b, v143
	v_exp_f32_e32 v147, v143
	s_nop 0
	v_lshlrev_b32_e32 v143, 16, v138
	v_and_b32_e32 v138, 0xffff0000, v138
	v_mul_f32_e32 v138, 0xbfb8aa3b, v138
	v_exp_f32_e32 v138, v138
	v_pk_add_f32 v[146:147], v[146:147], 1.0 op_sel_hi:[1,0]
	v_mul_f32_e32 v143, 0xbfb8aa3b, v143
	v_pk_mul_f32 v[144:145], v[144:145], v[146:147]
; DI float bflo(unsigned u) { return __uint_as_float(u << 16); }
; DI float bfhi(unsigned u) { return __uint_as_float(u & 0xffff0000u); }
; DI float sigmoidf(float x) { return __builtin_amdgcn_rcpf(1.f + __expf(-x)); }
; DI float inv_sigmoidf(float x) { return 1.f + __expf(-x); }
; __global__ void __launch_bounds__(512, 2) mega(Params p) {
;     ...
;       gemm8_epi(acc8, m0, n0, [&](int m, int n, f32x4& a) {
;         uint2 ua = *(const uint2*)(z + (size_t)m * ZS + C_MA + n);
;         uint2 ub = *(const uint2*)(z + (size_t)m * ZS + C_MB + n);
;         a[0] *= sigmoidf(bflo(ua.x)) * inv_sigmoidf(bflo(ub.x));
;         a[1] *= sigmoidf(bfhi(ua.x)) * inv_sigmoidf(bfhi(ub.x));
;         a[2] *= sigmoidf(bflo(ua.y)) * inv_sigmoidf(bflo(ub.y));
;         a[3] *= sigmoidf(bfhi(ua.y)) * inv_sigmoidf(bfhi(ub.y));
;       });
	v_add_f32_e32 v138, 1.0, v138
	v_pk_mul_f32 v[124:125], v[124:125], v[144:145]
	v_rcp_f32_e32 v145, v138
	s_nop 0
	v_and_b32_e32 v138, 0xffff0000, v140
	v_exp_f32_e32 v143, v143
	v_mul_f32_e32 v138, 0xbfb8aa3b, v138
	v_exp_f32_e32 v147, v138
	v_lshlrev_b32_e32 v138, 16, v139
	v_and_b32_e32 v139, 0xffff0000, v139
	v_mul_f32_e32 v138, 0xbfb8aa3b, v138
	v_mul_f32_e32 v139, 0xbfb8aa3b, v139
	v_exp_f32_e32 v138, v138
	v_exp_f32_e32 v139, v139
	v_add_f32_e32 v143, 1.0, v143
	v_rcp_f32_e32 v144, v143
	v_lshlrev_b32_e32 v143, 16, v140
	v_lshlrev_b32_e32 v140, 16, v141
	v_and_b32_e32 v141, 0xffff0000, v141
	v_mul_f32_e32 v140, 0xbfb8aa3b, v140
	v_mul_f32_e32 v141, 0xbfb8aa3b, v141
	v_add_f32_e32 v138, 1.0, v138
	v_exp_f32_e32 v140, v140
	v_add_f32_e32 v139, 1.0, v139
	v_exp_f32_e32 v141, v141
	v_rcp_f32_e32 v138, v138
	v_rcp_f32_e32 v139, v139
	v_mul_f32_e32 v143, 0xbfb8aa3b, v143
	v_exp_f32_e32 v146, v143
	v_pk_add_f32 v[140:141], v[140:141], 1.0 op_sel_hi:[1,0]
	v_pk_mul_f32 v[122:123], v[122:123], v[148:149]
	v_pk_mul_f32 v[138:139], v[138:139], v[140:141]
	v_pk_add_f32 v[146:147], v[146:147], 1.0 op_sel_hi:[1,0]
	v_pk_mul_f32 v[116:117], v[116:117], v[138:139]
	v_or_b32_e32 v138, 0x50, v142
	v_mad_i64_i32 v[140:141], s[26:27], v138, s35, v[136:137]
	v_pk_mul_f32 v[144:145], v[144:145], v[146:147]
	v_lshl_add_u64 v[138:139], v[140:141], 0, s[30:31]
	v_pk_mul_f32 v[114:115], v[114:115], v[144:145]
	v_lshl_add_u64 v[144:145], v[138:139], 0, v[0:1]
	s_waitcnt vmcnt(23)
	v_mov_b64_e32 v[144:145], v[230:231]
	v_lshl_add_u64 v[140:141], v[140:141], 0, s[42:43]
	v_lshl_add_u64 v[146:147], v[140:141], 0, v[0:1]
	s_waitcnt vmcnt(22)
	v_mov_b64_e32 v[146:147], v[232:233]
	s_nop 0
	v_lshlrev_b32_e32 v143, 16, v144
	v_mul_f32_e32 v143, 0xbfb8aa3b, v143
	v_exp_f32_e32 v143, v143
	s_nop 0
	v_add_f32_e32 v143, 1.0, v143
	v_rcp_f32_e32 v148, v143
	s_nop 0
	v_lshlrev_b32_e32 v143, 16, v146
	v_mul_f32_e32 v143, 0xbfb8aa3b, v143
	v_exp_f32_e32 v150, v143
	v_and_b32_e32 v143, 0xffff0000, v144
	v_mul_f32_e32 v143, 0xbfb8aa3b, v143
	v_exp_f32_e32 v143, v143
	s_nop 0
	v_add_f32_e32 v143, 1.0, v143
	v_rcp_f32_e32 v149, v143
	v_and_b32_e32 v143, 0xffff0000, v146
	v_mul_f32_e32 v143, 0xbfb8aa3b, v143
	v_exp_f32_e32 v151, v143
	v_lshlrev_b32_e32 v143, 16, v145
	v_mul_f32_e32 v143, 0xbfb8aa3b, v143
	v_exp_f32_e32 v143, v143
	v_pk_add_f32 v[150:151], v[150:151], 1.0 op_sel_hi:[1,0]
	v_add_f32_e32 v143, 1.0, v143
	v_rcp_f32_e32 v144, v143
	v_lshlrev_b32_e32 v143, 16, v147
	v_mul_f32_e32 v143, 0xbfb8aa3b, v143
	v_exp_f32_e32 v146, v143
	v_and_b32_e32 v143, 0xffff0000, v145
	v_mul_f32_e32 v143, 0xbfb8aa3b, v143
	v_exp_f32_e32 v143, v143
	v_pk_mul_f32 v[148:149], v[148:149], v[150:151]
	v_add_f32_e32 v143, 1.0, v143
	v_rcp_f32_e32 v145, v143
	v_and_b32_e32 v143, 0xffff0000, v147
	v_mul_f32_e32 v143, 0xbfb8aa3b, v143
	v_exp_f32_e32 v147, v143
	v_pk_mul_f32 v[106:107], v[106:107], v[148:149]
	v_pk_add_f32 v[146:147], v[146:147], 1.0 op_sel_hi:[1,0]
	s_nop 0
	v_pk_mul_f32 v[144:145], v[144:145], v[146:147]
	v_lshl_add_u64 v[146:147], v[140:141], 0, v[134:135]
	v_pk_mul_f32 v[108:109], v[108:109], v[144:145]
	v_lshl_add_u64 v[144:145], v[138:139], 0, v[134:135]
	s_waitcnt vmcnt(21)
	v_mov_b64_e32 v[144:145], v[234:235]
	s_nop 0
	s_waitcnt vmcnt(20)
	v_mov_b64_e32 v[146:147], v[236:237]
	s_nop 0
	v_lshlrev_b32_e32 v143, 16, v144
	v_mul_f32_e32 v143, 0xbfb8aa3b, v143
	v_exp_f32_e32 v143, v143
	s_nop 0
	v_add_f32_e32 v143, 1.0, v143
	v_rcp_f32_e32 v148, v143
	s_nop 0
	v_lshlrev_b32_e32 v143, 16, v146
	v_mul_f32_e32 v143, 0xbfb8aa3b, v143
	v_exp_f32_e32 v150, v143
	v_and_b32_e32 v143, 0xffff0000, v144
	v_mul_f32_e32 v143, 0xbfb8aa3b, v143
	v_exp_f32_e32 v143, v143
	s_nop 0
	v_add_f32_e32 v143, 1.0, v143
	v_rcp_f32_e32 v149, v143
	v_and_b32_e32 v143, 0xffff0000, v146
	v_mul_f32_e32 v143, 0xbfb8aa3b, v143
	v_exp_f32_e32 v151, v143
	v_lshlrev_b32_e32 v143, 16, v145
	v_mul_f32_e32 v143, 0xbfb8aa3b, v143
	v_exp_f32_e32 v143, v143
	v_pk_add_f32 v[150:151], v[150:151], 1.0 op_sel_hi:[1,0]
	v_add_f32_e32 v143, 1.0, v143
	v_rcp_f32_e32 v144, v143
	v_lshlrev_b32_e32 v143, 16, v147
	v_mul_f32_e32 v143, 0xbfb8aa3b, v143
	v_exp_f32_e32 v146, v143
	v_and_b32_e32 v143, 0xffff0000, v145
	v_mul_f32_e32 v143, 0xbfb8aa3b, v143
	v_exp_f32_e32 v143, v143
	v_pk_mul_f32 v[148:149], v[148:149], v[150:151]
	v_add_f32_e32 v143, 1.0, v143
	v_rcp_f32_e32 v145, v143
	v_and_b32_e32 v143, 0xffff0000, v147
	v_mul_f32_e32 v143, 0xbfb8aa3b, v143
	v_exp_f32_e32 v147, v143
	v_pk_mul_f32 v[98:99], v[98:99], v[148:149]
	v_pk_add_f32 v[146:147], v[146:147], 1.0 op_sel_hi:[1,0]
	s_nop 0
	v_pk_mul_f32 v[144:145], v[144:145], v[146:147]
	v_lshl_add_u64 v[146:147], v[140:141], 0, v[132:133]
	v_pk_mul_f32 v[100:101], v[100:101], v[144:145]
	v_lshl_add_u64 v[144:145], v[138:139], 0, v[132:133]
	s_waitcnt vmcnt(19)
	v_mov_b64_e32 v[144:145], v[238:239]
	v_lshl_add_u64 v[138:139], v[138:139], 0, v[130:131]
	s_waitcnt vmcnt(18)
	v_mov_b64_e32 v[146:147], v[240:241]
	v_lshl_add_u64 v[140:141], v[140:141], 0, v[130:131]
	s_waitcnt vmcnt(17)
	v_mov_b64_e32 v[138:139], v[242:243]
	s_nop 0
	s_waitcnt vmcnt(16)
; DI float bflo(unsigned u) { return __uint_as_float(u << 16); }
; DI float bfhi(unsigned u) { return __uint_as_float(u & 0xffff0000u); }
; DI float sigmoidf(float x) { return __builtin_amdgcn_rcpf(1.f + __expf(-x)); }
; DI float inv_sigmoidf(float x) { return 1.f + __expf(-x); }
; __global__ void __launch_bounds__(512, 2) mega(Params p) {
;     ...
;       gemm8_epi(acc8, m0, n0, [&](int m, int n, f32x4& a) {
;         uint2 ua = *(const uint2*)(z + (size_t)m * ZS + C_MA + n);
;         uint2 ub = *(const uint2*)(z + (size_t)m * ZS + C_MB + n);
;         a[0] *= sigmoidf(bflo(ua.x)) * inv_sigmoidf(bflo(ub.x));
;         a[1] *= sigmoidf(bfhi(ua.x)) * inv_sigmoidf(bfhi(ub.x));
;         a[2] *= sigmoidf(bflo(ua.y)) * inv_sigmoidf(bflo(ub.y));
;         a[3] *= sigmoidf(bfhi(ua.y)) * inv_sigmoidf(bfhi(ub.y));
;       });
	v_mov_b64_e32 v[140:141], v[244:245]
	s_nop 0
	v_lshlrev_b32_e32 v143, 16, v144
	v_mul_f32_e32 v143, 0xbfb8aa3b, v143
	v_exp_f32_e32 v143, v143
	s_nop 0
	v_add_f32_e32 v143, 1.0, v143
	v_rcp_f32_e32 v148, v143
	s_nop 0
	v_lshlrev_b32_e32 v143, 16, v146
	v_mul_f32_e32 v143, 0xbfb8aa3b, v143
	v_exp_f32_e32 v150, v143
	v_and_b32_e32 v143, 0xffff0000, v144
	v_mul_f32_e32 v143, 0xbfb8aa3b, v143
	v_exp_f32_e32 v143, v143
	s_nop 0
	v_add_f32_e32 v143, 1.0, v143
	v_rcp_f32_e32 v149, v143
	v_and_b32_e32 v143, 0xffff0000, v146
	v_mul_f32_e32 v143, 0xbfb8aa3b, v143
	v_exp_f32_e32 v151, v143
	v_lshlrev_b32_e32 v143, 16, v145
	v_mul_f32_e32 v143, 0xbfb8aa3b, v143
	v_exp_f32_e32 v143, v143
	v_pk_add_f32 v[150:151], v[150:151], 1.0 op_sel_hi:[1,0]
	v_add_f32_e32 v143, 1.0, v143
	v_rcp_f32_e32 v144, v143
	v_lshlrev_b32_e32 v143, 16, v147
	v_mul_f32_e32 v143, 0xbfb8aa3b, v143
	v_exp_f32_e32 v146, v143
	v_and_b32_e32 v143, 0xffff0000, v145
	v_mul_f32_e32 v143, 0xbfb8aa3b, v143
	v_exp_f32_e32 v143, v143
	v_pk_mul_f32 v[148:149], v[148:149], v[150:151]
	v_add_f32_e32 v143, 1.0, v143
	v_rcp_f32_e32 v145, v143
	v_and_b32_e32 v143, 0xffff0000, v147
	v_mul_f32_e32 v143, 0xbfb8aa3b, v143
	v_exp_f32_e32 v147, v143
	s_nop 0
	v_lshlrev_b32_e32 v143, 16, v138
	v_and_b32_e32 v138, 0xffff0000, v138
	v_mul_f32_e32 v138, 0xbfb8aa3b, v138
	v_exp_f32_e32 v138, v138
	v_pk_add_f32 v[146:147], v[146:147], 1.0 op_sel_hi:[1,0]
	v_mul_f32_e32 v143, 0xbfb8aa3b, v143
	v_pk_mul_f32 v[144:145], v[144:145], v[146:147]
	v_add_f32_e32 v138, 1.0, v138
	v_pk_mul_f32 v[92:93], v[92:93], v[144:145]
	v_rcp_f32_e32 v145, v138
	s_nop 0
	v_and_b32_e32 v138, 0xffff0000, v140
	v_exp_f32_e32 v143, v143
	v_mul_f32_e32 v138, 0xbfb8aa3b, v138
	v_exp_f32_e32 v147, v138
	v_lshlrev_b32_e32 v138, 16, v139
	v_and_b32_e32 v139, 0xffff0000, v139
	v_mul_f32_e32 v138, 0xbfb8aa3b, v138
	v_mul_f32_e32 v139, 0xbfb8aa3b, v139
	v_exp_f32_e32 v138, v138
	v_exp_f32_e32 v139, v139
	v_add_f32_e32 v143, 1.0, v143
	v_rcp_f32_e32 v144, v143
	v_lshlrev_b32_e32 v143, 16, v140
	v_lshlrev_b32_e32 v140, 16, v141
	v_and_b32_e32 v141, 0xffff0000, v141
	v_mul_f32_e32 v140, 0xbfb8aa3b, v140
	v_mul_f32_e32 v141, 0xbfb8aa3b, v141
	v_add_f32_e32 v138, 1.0, v138
	v_exp_f32_e32 v140, v140
	v_add_f32_e32 v139, 1.0, v139
	v_exp_f32_e32 v141, v141
	v_rcp_f32_e32 v138, v138
	v_rcp_f32_e32 v139, v139
	v_mul_f32_e32 v143, 0xbfb8aa3b, v143
	v_exp_f32_e32 v146, v143
	v_pk_add_f32 v[140:141], v[140:141], 1.0 op_sel_hi:[1,0]
	v_pk_mul_f32 v[90:91], v[90:91], v[148:149]
	v_pk_mul_f32 v[138:139], v[138:139], v[140:141]
	v_pk_add_f32 v[146:147], v[146:147], 1.0 op_sel_hi:[1,0]
	v_pk_mul_f32 v[84:85], v[84:85], v[138:139]
	v_or_b32_e32 v138, 0x60, v142
	v_mad_i64_i32 v[140:141], s[26:27], v138, s35, v[136:137]
	v_pk_mul_f32 v[144:145], v[144:145], v[146:147]
	v_lshl_add_u64 v[138:139], v[140:141], 0, s[30:31]
	v_pk_mul_f32 v[82:83], v[82:83], v[144:145]
	v_lshl_add_u64 v[144:145], v[138:139], 0, v[0:1]
	s_waitcnt vmcnt(15)
	v_mov_b64_e32 v[144:145], v[198:199]
	v_lshl_add_u64 v[140:141], v[140:141], 0, s[42:43]
	v_lshl_add_u64 v[146:147], v[140:141], 0, v[0:1]
	s_waitcnt vmcnt(14)
	v_mov_b64_e32 v[146:147], v[200:201]
	s_nop 0
	v_lshlrev_b32_e32 v143, 16, v144
	v_mul_f32_e32 v143, 0xbfb8aa3b, v143
	v_exp_f32_e32 v143, v143
	s_nop 0
	v_add_f32_e32 v143, 1.0, v143
	v_rcp_f32_e32 v148, v143
	s_nop 0
	v_lshlrev_b32_e32 v143, 16, v146
	v_mul_f32_e32 v143, 0xbfb8aa3b, v143
	v_exp_f32_e32 v150, v143
	v_and_b32_e32 v143, 0xffff0000, v144
	v_mul_f32_e32 v143, 0xbfb8aa3b, v143
	v_exp_f32_e32 v143, v143
	s_nop 0
	v_add_f32_e32 v143, 1.0, v143
	v_rcp_f32_e32 v149, v143
	v_and_b32_e32 v143, 0xffff0000, v146
	v_mul_f32_e32 v143, 0xbfb8aa3b, v143
	v_exp_f32_e32 v151, v143
	v_lshlrev_b32_e32 v143, 16, v145
	v_mul_f32_e32 v143, 0xbfb8aa3b, v143
	v_exp_f32_e32 v143, v143
	v_pk_add_f32 v[150:151], v[150:151], 1.0 op_sel_hi:[1,0]
	v_add_f32_e32 v143, 1.0, v143
	v_rcp_f32_e32 v144, v143
	v_lshlrev_b32_e32 v143, 16, v147
	v_mul_f32_e32 v143, 0xbfb8aa3b, v143
	v_exp_f32_e32 v146, v143
	v_and_b32_e32 v143, 0xffff0000, v145
	v_mul_f32_e32 v143, 0xbfb8aa3b, v143
	v_exp_f32_e32 v143, v143
	v_pk_mul_f32 v[148:149], v[148:149], v[150:151]
	v_add_f32_e32 v143, 1.0, v143
	v_rcp_f32_e32 v145, v143
	v_and_b32_e32 v143, 0xffff0000, v147
	v_mul_f32_e32 v143, 0xbfb8aa3b, v143
	v_exp_f32_e32 v147, v143
	v_pk_mul_f32 v[74:75], v[74:75], v[148:149]
	v_pk_add_f32 v[146:147], v[146:147], 1.0 op_sel_hi:[1,0]
	s_nop 0
	v_pk_mul_f32 v[144:145], v[144:145], v[146:147]
	v_lshl_add_u64 v[146:147], v[140:141], 0, v[134:135]
	v_pk_mul_f32 v[76:77], v[76:77], v[144:145]
	v_lshl_add_u64 v[144:145], v[138:139], 0, v[134:135]
	s_waitcnt vmcnt(13)
	v_mov_b64_e32 v[144:145], v[202:203]
	s_nop 0
	s_waitcnt vmcnt(12)
	v_mov_b64_e32 v[146:147], v[204:205]
	s_nop 0
	v_lshlrev_b32_e32 v143, 16, v144
	v_mul_f32_e32 v143, 0xbfb8aa3b, v143
	v_exp_f32_e32 v143, v143
	s_nop 0
	v_add_f32_e32 v143, 1.0, v143
	v_rcp_f32_e32 v148, v143
	s_nop 0
	v_lshlrev_b32_e32 v143, 16, v146
	v_mul_f32_e32 v143, 0xbfb8aa3b, v143
	v_exp_f32_e32 v150, v143
	v_and_b32_e32 v143, 0xffff0000, v144
	v_mul_f32_e32 v143, 0xbfb8aa3b, v143
	v_exp_f32_e32 v143, v143
	s_nop 0
	v_add_f32_e32 v143, 1.0, v143
	v_rcp_f32_e32 v149, v143
	v_and_b32_e32 v143, 0xffff0000, v146
	v_mul_f32_e32 v143, 0xbfb8aa3b, v143
	v_exp_f32_e32 v151, v143
	v_lshlrev_b32_e32 v143, 16, v145
	v_mul_f32_e32 v143, 0xbfb8aa3b, v143
	v_exp_f32_e32 v143, v143
	v_pk_add_f32 v[150:151], v[150:151], 1.0 op_sel_hi:[1,0]
	v_add_f32_e32 v143, 1.0, v143
	v_rcp_f32_e32 v144, v143
	v_lshlrev_b32_e32 v143, 16, v147
	v_mul_f32_e32 v143, 0xbfb8aa3b, v143
	v_exp_f32_e32 v146, v143
	v_and_b32_e32 v143, 0xffff0000, v145
	v_mul_f32_e32 v143, 0xbfb8aa3b, v143
	v_exp_f32_e32 v143, v143
	v_pk_mul_f32 v[148:149], v[148:149], v[150:151]
	v_add_f32_e32 v143, 1.0, v143
	v_rcp_f32_e32 v145, v143
	v_and_b32_e32 v143, 0xffff0000, v147
	v_mul_f32_e32 v143, 0xbfb8aa3b, v143
	v_exp_f32_e32 v147, v143
	v_pk_mul_f32 v[66:67], v[66:67], v[148:149]
	v_pk_add_f32 v[146:147], v[146:147], 1.0 op_sel_hi:[1,0]
	s_nop 0
	v_pk_mul_f32 v[144:145], v[144:145], v[146:147]
	v_lshl_add_u64 v[146:147], v[140:141], 0, v[132:133]
	v_pk_mul_f32 v[68:69], v[68:69], v[144:145]
	v_lshl_add_u64 v[144:145], v[138:139], 0, v[132:133]
	s_waitcnt vmcnt(11)
; DI float bflo(unsigned u) { return __uint_as_float(u << 16); }
; DI float bfhi(unsigned u) { return __uint_as_float(u & 0xffff0000u); }
; DI float sigmoidf(float x) { return __builtin_amdgcn_rcpf(1.f + __expf(-x)); }
; DI float inv_sigmoidf(float x) { return 1.f + __expf(-x); }
; __global__ void __launch_bounds__(512, 2) mega(Params p) {
;     ...
;       gemm8_epi(acc8, m0, n0, [&](int m, int n, f32x4& a) {
;         uint2 ua = *(const uint2*)(z + (size_t)m * ZS + C_MA + n);
;         uint2 ub = *(const uint2*)(z + (size_t)m * ZS + C_MB + n);
;         a[0] *= sigmoidf(bflo(ua.x)) * inv_sigmoidf(bflo(ub.x));
;         a[1] *= sigmoidf(bfhi(ua.x)) * inv_sigmoidf(bfhi(ub.x));
;         a[2] *= sigmoidf(bflo(ua.y)) * inv_sigmoidf(bflo(ub.y));
;         a[3] *= sigmoidf(bfhi(ua.y)) * inv_sigmoidf(bfhi(ub.y));
;       });
	v_mov_b64_e32 v[144:145], v[206:207]
	v_lshl_add_u64 v[138:139], v[138:139], 0, v[130:131]
	s_waitcnt vmcnt(10)
	v_mov_b64_e32 v[146:147], v[208:209]
	v_lshl_add_u64 v[140:141], v[140:141], 0, v[130:131]
	s_waitcnt vmcnt(9)
	v_mov_b64_e32 v[138:139], v[210:211]
	s_nop 0
	s_waitcnt vmcnt(8)
	v_mov_b64_e32 v[140:141], v[212:213]
	s_nop 0
	v_lshlrev_b32_e32 v143, 16, v144
	v_mul_f32_e32 v143, 0xbfb8aa3b, v143
	v_exp_f32_e32 v143, v143
	s_nop 0
	v_add_f32_e32 v143, 1.0, v143
	v_rcp_f32_e32 v148, v143
	s_nop 0
	v_lshlrev_b32_e32 v143, 16, v146
	v_mul_f32_e32 v143, 0xbfb8aa3b, v143
	v_exp_f32_e32 v150, v143
	v_and_b32_e32 v143, 0xffff0000, v144
	v_mul_f32_e32 v143, 0xbfb8aa3b, v143
	v_exp_f32_e32 v143, v143
	s_nop 0
	v_add_f32_e32 v143, 1.0, v143
	v_rcp_f32_e32 v149, v143
	v_and_b32_e32 v143, 0xffff0000, v146
	v_mul_f32_e32 v143, 0xbfb8aa3b, v143
	v_exp_f32_e32 v151, v143
	v_lshlrev_b32_e32 v143, 16, v145
	v_mul_f32_e32 v143, 0xbfb8aa3b, v143
	v_exp_f32_e32 v143, v143
	v_pk_add_f32 v[150:151], v[150:151], 1.0 op_sel_hi:[1,0]
	v_add_f32_e32 v143, 1.0, v143
	v_rcp_f32_e32 v144, v143
	v_lshlrev_b32_e32 v143, 16, v147
	v_mul_f32_e32 v143, 0xbfb8aa3b, v143
	v_exp_f32_e32 v146, v143
	v_and_b32_e32 v143, 0xffff0000, v145
	v_mul_f32_e32 v143, 0xbfb8aa3b, v143
	v_exp_f32_e32 v143, v143
	v_pk_mul_f32 v[148:149], v[148:149], v[150:151]
	v_add_f32_e32 v143, 1.0, v143
	v_rcp_f32_e32 v145, v143
	v_and_b32_e32 v143, 0xffff0000, v147
	v_mul_f32_e32 v143, 0xbfb8aa3b, v143
	v_exp_f32_e32 v147, v143
	s_nop 0
	v_lshlrev_b32_e32 v143, 16, v138
	v_and_b32_e32 v138, 0xffff0000, v138
	v_mul_f32_e32 v138, 0xbfb8aa3b, v138
	v_exp_f32_e32 v138, v138
	v_pk_add_f32 v[146:147], v[146:147], 1.0 op_sel_hi:[1,0]
	v_mul_f32_e32 v143, 0xbfb8aa3b, v143
	v_pk_mul_f32 v[144:145], v[144:145], v[146:147]
	v_add_f32_e32 v138, 1.0, v138
	v_pk_mul_f32 v[60:61], v[60:61], v[144:145]
	v_rcp_f32_e32 v145, v138
	s_nop 0
	v_and_b32_e32 v138, 0xffff0000, v140
	v_exp_f32_e32 v143, v143
	v_mul_f32_e32 v138, 0xbfb8aa3b, v138
	v_exp_f32_e32 v147, v138
	v_lshlrev_b32_e32 v138, 16, v139
	v_and_b32_e32 v139, 0xffff0000, v139
	v_mul_f32_e32 v138, 0xbfb8aa3b, v138
	v_mul_f32_e32 v139, 0xbfb8aa3b, v139
	v_exp_f32_e32 v138, v138
	v_exp_f32_e32 v139, v139
	v_add_f32_e32 v143, 1.0, v143
	v_rcp_f32_e32 v144, v143
	v_lshlrev_b32_e32 v143, 16, v140
	v_lshlrev_b32_e32 v140, 16, v141
	v_and_b32_e32 v141, 0xffff0000, v141
	v_mul_f32_e32 v140, 0xbfb8aa3b, v140
	v_mul_f32_e32 v141, 0xbfb8aa3b, v141
	v_add_f32_e32 v138, 1.0, v138
	v_exp_f32_e32 v140, v140
	v_add_f32_e32 v139, 1.0, v139
	v_exp_f32_e32 v141, v141
	v_rcp_f32_e32 v138, v138
	v_rcp_f32_e32 v139, v139
	v_mul_f32_e32 v143, 0xbfb8aa3b, v143
	v_pk_add_f32 v[140:141], v[140:141], 1.0 op_sel_hi:[1,0]
	v_exp_f32_e32 v146, v143
	v_pk_mul_f32 v[138:139], v[138:139], v[140:141]
	v_pk_mul_f32 v[58:59], v[58:59], v[148:149]
	v_pk_mul_f32 v[52:53], v[52:53], v[138:139]
	v_or_b32_e32 v138, 0x70, v142
	v_mad_i64_i32 v[138:139], s[26:27], v138, s35, v[136:137]
	v_lshl_add_u64 v[136:137], v[138:139], 0, s[30:31]
	v_lshl_add_u64 v[140:141], v[136:137], 0, v[0:1]
	s_waitcnt vmcnt(7)
	v_mov_b64_e32 v[140:141], v[214:215]
	v_lshl_add_u64 v[138:139], v[138:139], 0, s[42:43]
	v_lshl_add_u64 v[142:143], v[138:139], 0, v[0:1]
	s_waitcnt vmcnt(6)
	v_mov_b64_e32 v[142:143], v[216:217]
	v_pk_add_f32 v[146:147], v[146:147], 1.0 op_sel_hi:[1,0]
	s_nop 0
	v_lshlrev_b32_e32 v0, 16, v140
	v_mul_f32_e32 v0, 0xbfb8aa3b, v0
	v_exp_f32_e32 v0, v0
	v_pk_mul_f32 v[144:145], v[144:145], v[146:147]
	v_add_f32_e32 v0, 1.0, v0
	v_pk_mul_f32 v[50:51], v[50:51], v[144:145]
	v_rcp_f32_e32 v144, v0
	s_nop 0
	v_lshlrev_b32_e32 v0, 16, v142
	v_mul_f32_e32 v0, 0xbfb8aa3b, v0
	v_exp_f32_e32 v146, v0
	v_and_b32_e32 v0, 0xffff0000, v140
	v_mul_f32_e32 v0, 0xbfb8aa3b, v0
	v_exp_f32_e32 v0, v0
	s_nop 0
	v_add_f32_e32 v0, 1.0, v0
	v_rcp_f32_e32 v145, v0
	v_and_b32_e32 v0, 0xffff0000, v142
	v_mul_f32_e32 v0, 0xbfb8aa3b, v0
	v_exp_f32_e32 v147, v0
	v_lshlrev_b32_e32 v0, 16, v141
	v_mul_f32_e32 v0, 0xbfb8aa3b, v0
	v_exp_f32_e32 v0, v0
	v_pk_add_f32 v[146:147], v[146:147], 1.0 op_sel_hi:[1,0]
	v_add_f32_e32 v0, 1.0, v0
	v_rcp_f32_e32 v140, v0
	v_lshlrev_b32_e32 v0, 16, v143
	v_mul_f32_e32 v0, 0xbfb8aa3b, v0
	v_exp_f32_e32 v142, v0
	v_and_b32_e32 v0, 0xffff0000, v141
	v_mul_f32_e32 v0, 0xbfb8aa3b, v0
	v_exp_f32_e32 v0, v0
	v_pk_mul_f32 v[144:145], v[144:145], v[146:147]
	v_add_f32_e32 v0, 1.0, v0
	v_rcp_f32_e32 v141, v0
	v_and_b32_e32 v0, 0xffff0000, v143
	v_mul_f32_e32 v0, 0xbfb8aa3b, v0
	v_exp_f32_e32 v143, v0
	v_pk_mul_f32 v[42:43], v[42:43], v[144:145]
	v_pk_add_f32 v[142:143], v[142:143], 1.0 op_sel_hi:[1,0]
	s_nop 0
	v_pk_mul_f32 v[140:141], v[140:141], v[142:143]
	s_nop 0
	v_pk_mul_f32 v[44:45], v[44:45], v[140:141]
	v_lshl_add_u64 v[140:141], v[136:137], 0, v[134:135]
	s_waitcnt vmcnt(5)
	v_mov_b64_e32 v[140:141], v[218:219]
	v_lshl_add_u64 v[134:135], v[138:139], 0, v[134:135]
	s_waitcnt vmcnt(4)
; DI float bflo(unsigned u) { return __uint_as_float(u << 16); }
; DI float bfhi(unsigned u) { return __uint_as_float(u & 0xffff0000u); }
; DI float sigmoidf(float x) { return __builtin_amdgcn_rcpf(1.f + __expf(-x)); }
; DI float inv_sigmoidf(float x) { return 1.f + __expf(-x); }
; __global__ void __launch_bounds__(512, 2) mega(Params p) {
;     ...
;       gemm8_epi(acc8, m0, n0, [&](int m, int n, f32x4& a) {
;         uint2 ua = *(const uint2*)(z + (size_t)m * ZS + C_MA + n);
;         uint2 ub = *(const uint2*)(z + (size_t)m * ZS + C_MB + n);
;         a[0] *= sigmoidf(bflo(ua.x)) * inv_sigmoidf(bflo(ub.x));
;         a[1] *= sigmoidf(bfhi(ua.x)) * inv_sigmoidf(bfhi(ub.x));
;         a[2] *= sigmoidf(bflo(ua.y)) * inv_sigmoidf(bflo(ub.y));
;         a[3] *= sigmoidf(bfhi(ua.y)) * inv_sigmoidf(bfhi(ub.y));
;       });
	v_mov_b64_e32 v[134:135], v[220:221]
	s_nop 0
	v_lshlrev_b32_e32 v0, 16, v140
	v_mul_f32_e32 v0, 0xbfb8aa3b, v0
	v_exp_f32_e32 v0, v0
	s_nop 0
	v_add_f32_e32 v0, 1.0, v0
	v_rcp_f32_e32 v142, v0
	s_nop 0
	v_lshlrev_b32_e32 v0, 16, v134
	v_mul_f32_e32 v0, 0xbfb8aa3b, v0
	v_exp_f32_e32 v144, v0
	v_and_b32_e32 v0, 0xffff0000, v140
	v_mul_f32_e32 v0, 0xbfb8aa3b, v0
	v_exp_f32_e32 v0, v0
	s_nop 0
	v_add_f32_e32 v0, 1.0, v0
	v_rcp_f32_e32 v143, v0
	v_and_b32_e32 v0, 0xffff0000, v134
	v_mul_f32_e32 v0, 0xbfb8aa3b, v0
	v_exp_f32_e32 v145, v0
	v_lshlrev_b32_e32 v0, 16, v141
	v_mul_f32_e32 v0, 0xbfb8aa3b, v0
	v_exp_f32_e32 v0, v0
	v_pk_add_f32 v[144:145], v[144:145], 1.0 op_sel_hi:[1,0]
	v_add_f32_e32 v0, 1.0, v0
	v_rcp_f32_e32 v140, v0
	v_lshlrev_b32_e32 v0, 16, v135
	v_mul_f32_e32 v0, 0xbfb8aa3b, v0
	v_exp_f32_e32 v134, v0
	v_and_b32_e32 v0, 0xffff0000, v141
	v_mul_f32_e32 v0, 0xbfb8aa3b, v0
	v_exp_f32_e32 v0, v0
	v_pk_mul_f32 v[142:143], v[142:143], v[144:145]
	v_mov_b32_e32 v145, v1
	v_pk_mul_f32 v[34:35], v[34:35], v[142:143]
	v_add_f32_e32 v0, 1.0, v0
	v_rcp_f32_e32 v141, v0
	v_and_b32_e32 v0, 0xffff0000, v135
	v_mul_f32_e32 v0, 0xbfb8aa3b, v0
	v_exp_f32_e32 v135, v0
	s_nop 0
	v_pk_add_f32 v[134:135], v[134:135], 1.0 op_sel_hi:[1,0]
	s_nop 0
	v_pk_mul_f32 v[134:135], v[140:141], v[134:135]
	s_nop 0
	v_pk_mul_f32 v[36:37], v[36:37], v[134:135]
	v_lshl_add_u64 v[134:135], v[136:137], 0, v[132:133]
	s_waitcnt vmcnt(3)
	v_mov_b64_e32 v[134:135], v[222:223]
	v_lshl_add_u64 v[132:133], v[138:139], 0, v[132:133]
	s_waitcnt vmcnt(2)
	v_mov_b64_e32 v[132:133], v[224:225]
	s_nop 0
	v_lshlrev_b32_e32 v0, 16, v134
	v_mul_f32_e32 v0, 0xbfb8aa3b, v0
	v_exp_f32_e32 v0, v0
	s_nop 0
	v_add_f32_e32 v0, 1.0, v0
	v_rcp_f32_e32 v140, v0
	s_nop 0
	v_lshlrev_b32_e32 v0, 16, v132
	v_mul_f32_e32 v0, 0xbfb8aa3b, v0
	v_exp_f32_e32 v142, v0
	v_and_b32_e32 v0, 0xffff0000, v134
	v_mul_f32_e32 v0, 0xbfb8aa3b, v0
	v_exp_f32_e32 v0, v0
	s_nop 0
	v_add_f32_e32 v0, 1.0, v0
	v_rcp_f32_e32 v141, v0
	v_and_b32_e32 v0, 0xffff0000, v132
	v_mul_f32_e32 v0, 0xbfb8aa3b, v0
	v_exp_f32_e32 v143, v0
	v_lshlrev_b32_e32 v0, 16, v135
	v_mul_f32_e32 v0, 0xbfb8aa3b, v0
	v_exp_f32_e32 v0, v0
	v_pk_add_f32 v[142:143], v[142:143], 1.0 op_sel_hi:[1,0]
	v_add_f32_e32 v0, 1.0, v0
	v_rcp_f32_e32 v134, v0
	v_lshlrev_b32_e32 v0, 16, v133
	v_mul_f32_e32 v0, 0xbfb8aa3b, v0
	v_exp_f32_e32 v132, v0
	v_and_b32_e32 v0, 0xffff0000, v135
	v_mul_f32_e32 v0, 0xbfb8aa3b, v0
	v_exp_f32_e32 v0, v0
	v_pk_mul_f32 v[140:141], v[140:141], v[142:143]
	v_mov_b32_e32 v143, v1
	v_pk_mul_f32 v[26:27], v[26:27], v[140:141]
	v_add_f32_e32 v0, 1.0, v0
	v_rcp_f32_e32 v135, v0
	v_and_b32_e32 v0, 0xffff0000, v133
	v_mul_f32_e32 v0, 0xbfb8aa3b, v0
	v_exp_f32_e32 v133, v0
	s_nop 0
	v_pk_add_f32 v[132:133], v[132:133], 1.0 op_sel_hi:[1,0]
	s_nop 0
	v_pk_mul_f32 v[132:133], v[134:135], v[132:133]
	s_nop 0
	v_pk_mul_f32 v[28:29], v[28:29], v[132:133]
	v_lshl_add_u64 v[132:133], v[136:137], 0, v[130:131]
	s_waitcnt vmcnt(1)
	v_mov_b64_e32 v[132:133], v[226:227]
	v_lshl_add_u64 v[130:131], v[138:139], 0, v[130:131]
	s_waitcnt vmcnt(0)
; DI float bflo(unsigned u) { return __uint_as_float(u << 16); }
; DI float bfhi(unsigned u) { return __uint_as_float(u & 0xffff0000u); }
; DI float sigmoidf(float x) { return __builtin_amdgcn_rcpf(1.f + __expf(-x)); }
; DI float inv_sigmoidf(float x) { return 1.f + __expf(-x); }
; DI int TID8() { int t = threadIdx.x; asm volatile("" : "+v"(t)); return t; }
; DI void gemm8_accum(f32x4 (&acc)[8][4], const bf16_t* a, size_t lda, const bf16_t* b, size_t ldb, int nkb, bf16_t* L,
;                     const bool pre, const bf16_t* an, size_t ldan, const bf16_t* bn, size_t ldbn) {
;   const int tid = TID8(), lane = tid & 63, w = tid >> 6;
;   const int wm = w >> 2, wn = w & 3;
;   const int lrow = tid >> 3, lch = tid & 7;
;   u32x4 ra[4], rb[4];
;   unsigned offa[4], offb[4];
; #pragma unroll
;   for (int i = 0; i < 4; ++i) {
;     offa[i] = (unsigned)(lrow + 64 * i) * (unsigned)lda + (unsigned)(lch * 8);
;     offb[i] = (unsigned)(lrow + 64 * i) * (unsigned)ldb + (unsigned)(lch * 8);
;   }
;   if (!pre) {
;     g8_load1o(ra, a, offa);
;     g8_load1o(rb, b, offb);
;     __syncthreads();
;     g8_store(L, ra, rb, lrow, lch);
;   }
;   g8_load1o(ra, a + 64, offa);
;   g8_load1o(rb, b + 64, offb);
; __global__ void __launch_bounds__(512, 2) mega(Params p) {
;     ...
;       gemm8_epi(acc8, m0, n0, [&](int m, int n, f32x4& a) {
;         uint2 ua = *(const uint2*)(z + (size_t)m * ZS + C_MA + n);
;         uint2 ub = *(const uint2*)(z + (size_t)m * ZS + C_MB + n);
;         a[0] *= sigmoidf(bflo(ua.x)) * inv_sigmoidf(bflo(ub.x));
;         a[1] *= sigmoidf(bfhi(ua.x)) * inv_sigmoidf(bfhi(ub.x));
;         a[2] *= sigmoidf(bflo(ua.y)) * inv_sigmoidf(bflo(ub.y));
;         a[3] *= sigmoidf(bfhi(ua.y)) * inv_sigmoidf(bfhi(ub.y));
	v_mov_b64_e32 v[130:131], v[228:229]
	v_mov_b32_e32 v139, v1
	v_ashrrev_i32_e32 v173, 3, v172
	v_lshrrev_b32_e32 v140, 1, v173
	v_xor_b32_e32 v140, v140, v172
	v_lshlrev_b32_e32 v140, 3, v140
	v_and_b32_e32 v174, 56, v140
	v_lshrrev_b32_e32 v175, 1, v172
	v_bfe_u32 v176, v172, 1, 3
	v_lshlrev_b32_e32 v191, 1, v174
	v_lshlrev_b32_e32 v163, 6, v173
	s_nop 0
	v_lshlrev_b32_e32 v0, 16, v132
	v_mul_f32_e32 v0, 0xbfb8aa3b, v0
	v_exp_f32_e32 v0, v0
	s_nop 0
	v_add_f32_e32 v0, 1.0, v0
	v_rcp_f32_e32 v134, v0
	s_nop 0
	v_lshlrev_b32_e32 v0, 16, v130
	v_mul_f32_e32 v0, 0xbfb8aa3b, v0
	v_exp_f32_e32 v136, v0
	v_and_b32_e32 v0, 0xffff0000, v132
	v_mul_f32_e32 v0, 0xbfb8aa3b, v0
	v_exp_f32_e32 v0, v0
	s_nop 0
	v_add_f32_e32 v0, 1.0, v0
	v_rcp_f32_e32 v135, v0
	v_and_b32_e32 v0, 0xffff0000, v130
	v_mul_f32_e32 v0, 0xbfb8aa3b, v0
	v_exp_f32_e32 v137, v0
	v_lshlrev_b32_e32 v0, 16, v133
	v_mul_f32_e32 v0, 0xbfb8aa3b, v0
	v_exp_f32_e32 v0, v0
	v_pk_add_f32 v[136:137], v[136:137], 1.0 op_sel_hi:[1,0]
	v_add_f32_e32 v0, 1.0, v0
	v_rcp_f32_e32 v132, v0
	v_lshlrev_b32_e32 v0, 16, v131
	v_mul_f32_e32 v0, 0xbfb8aa3b, v0
	v_exp_f32_e32 v130, v0
	v_and_b32_e32 v0, 0xffff0000, v133
	v_mul_f32_e32 v0, 0xbfb8aa3b, v0
	v_exp_f32_e32 v0, v0
	v_pk_mul_f32 v[134:135], v[134:135], v[136:137]
	v_mov_b32_e32 v137, v1
	v_pk_mul_f32 v[18:19], v[18:19], v[134:135]
	v_add_f32_e32 v0, 1.0, v0
	v_rcp_f32_e32 v133, v0
	v_and_b32_e32 v0, 0xffff0000, v131
	v_mul_f32_e32 v0, 0xbfb8aa3b, v0
	v_exp_f32_e32 v131, v0
	v_lshlrev_b32_e32 v0, 3, v172
	v_and_b32_e32 v0, 56, v0
	v_mov_b32_e32 v135, v1
	v_pk_add_f32 v[130:131], v[130:131], 1.0 op_sel_hi:[1,0]
	s_nop 0
	v_pk_mul_f32 v[130:131], v[132:133], v[130:131]
	v_lshl_or_b32 v132, v173, 9, v0
	v_pk_mul_f32 v[20:21], v[20:21], v[130:131]
	v_mad_u64_u32 v[130:131], s[26:27], v173, s25, v[0:1]
	v_mov_b32_e32 v131, v1
	v_add_u32_e32 v144, 0x18000, v132
	v_add_u32_e32 v0, 0x54600, v130
	v_add_u32_e32 v142, 0x10000, v132
	v_lshlrev_b64 v[186:187], 1, v[130:131]
	v_lshlrev_b64 v[170:171], 1, v[144:145]
	v_add_u32_e32 v136, 0xa8c00, v130
	v_add_u32_e32 v138, 0xfd200, v130
	v_lshl_add_u64 v[130:131], s[2:3], 0, v[186:187]
	v_lshlrev_b64 v[184:185], 1, v[0:1]
	v_lshlrev_b64 v[168:169], 1, v[142:143]
	v_lshl_add_u64 v[142:143], s[6:7], 0, v[170:171]
	global_load_dwordx4 v[146:149], v[130:131], off offset:2736
	v_lshlrev_b64 v[182:183], 1, v[136:137]
	global_load_dwordx4 v[142:145], v[142:143], off offset:128
	v_lshl_add_u64 v[130:131], s[2:3], 0, v[184:185]
	v_add_u32_e32 v134, 0x8000, v132
	v_mov_b32_e32 v133, v1
	global_load_dwordx4 v[150:153], v[130:131], off offset:2736
	v_lshl_add_u64 v[130:131], s[2:3], 0, v[182:183]
	v_lshlrev_b64 v[180:181], 1, v[138:139]
	global_load_dwordx4 v[154:157], v[130:131], off offset:2736
	v_lshl_add_u64 v[130:131], s[2:3], 0, v[180:181]
	v_lshlrev_b64 v[164:165], 1, v[132:133]
	v_lshlrev_b64 v[166:167], 1, v[134:135]
	global_load_dwordx4 v[158:161], v[130:131], off offset:2736
	v_lshl_add_u64 v[130:131], s[6:7], 0, v[164:165]
	v_lshl_add_u64 v[134:135], s[6:7], 0, v[166:167]
	global_load_dwordx4 v[130:133], v[130:131], off offset:128
	v_bfe_u32 v0, v172, 4, 2
	global_load_dwordx4 v[138:141], v[134:135], off offset:128
	v_lshl_add_u64 v[134:135], s[6:7], 0, v[168:169]
	global_load_dwordx4 v[134:137], v[134:135], off offset:128
	v_bitop3_b32 v175, v175, v0, 7 bitop3:0x6c
	v_lshlrev_b32_e32 v192, 3, v175
	v_lshlrev_b32_e32 v175, 5, v172
	v_and_b32_e32 v175, 0xffffe000, v175
	v_lshlrev_b32_e32 v172, 6, v172
	v_and_or_b32 v188, v172, s1, v175
	v_readlane_b32 s1, v254, 20
	s_add_u32 s2, s1, s21
	v_readlane_b32 s1, v254, 21
	s_addc_u32 s3, s1, 0
	v_readlane_b32 s1, v254, 22
	v_bitop3_b32 v0, v0, v176, 4 bitop3:0x36
	s_add_u32 s0, s1, s0
	v_readlane_b32 s1, v254, 23
	v_and_b32_e32 v193, 0x33c0, v172
	v_lshlrev_b32_e32 v190, 3, v0
	v_lshlrev_b32_e32 v0, 7, v173
	s_addc_u32 s1, s1, 0
	v_add3_u32 v0, 0, v191, v0
	v_lshl_add_u64 v[172:173], s[2:3], 0, v[170:171]
	v_lshl_add_u64 v[174:175], s[2:3], 0, v[168:169]
	v_lshl_add_u64 v[176:177], s[2:3], 0, v[166:167]
	v_lshl_add_u64 v[178:179], s[2:3], 0, v[164:165]
	v_lshl_add_u64 v[180:181], s[0:1], 0, v[180:181]
	v_lshl_add_u64 v[182:183], s[0:1], 0, v[182:183]
	v_lshl_add_u64 v[184:185], s[0:1], 0, v[184:185]
	v_lshl_add_u64 v[186:187], s[0:1], 0, v[186:187]
	s_mov_b64 s[0:1], 0
	s_mov_b32 s2, 0
	v_lshlrev_b32_e32 v189, 1, v188
	v_lshlrev_b32_e32 v188, 1, v193
	v_readfirstlane_b32 s52, v186
	v_readfirstlane_b32 s53, v187
	s_sub_u32 s52, s52, 0x40000000
	s_subb_u32 s53, s53, 0
	v_readfirstlane_b32 s56, v178
	v_readfirstlane_b32 s57, v179
	s_sub_u32 s56, s56, 0x40000000
	s_subb_u32 s57, s57, 0
	v_subrev_u32_e32 v187, s52, v186
	v_subrev_u32_e32 v185, s52, v184
	v_subrev_u32_e32 v183, s52, v182
	v_subrev_u32_e32 v181, s52, v180
	v_subrev_u32_e32 v179, s56, v178
	v_subrev_u32_e32 v177, s56, v176
	v_subrev_u32_e32 v175, s56, v174
	v_subrev_u32_e32 v173, s56, v172
